# GEMM K-loops: tail ALU/loop-control instrs moved from after the last MFMA into MFMA shadows; duplicate lgkmcnt(0) removed (on top of peel + ret_out load edits)
# speedup vs baseline: 1.0257x; 1.0184x over previous
; #define PG8_STAGE(bufoff, gbase, voff) do { _Pragma("unroll") for (int _i = 0; _i < 2; ++_i) \
;         __builtin_amdgcn_global_load_lds((const unsigned*)((const char*)(gbase) + (voff)[_i]), (LAS unsigned*)(lds + (bufoff) + ldsw + _i * 8192), 16, 0, 0); } while (0)
; #define PG8_LDA(dst, b, h) do { _Pragma("unroll") for (int m = 0; m < 4; ++m) _Pragma("unroll") for (int k = 0; k < 2; ++k) dst[m][k] = *(const LAS bf16x8*)(lds + PG8_SA(b, h) + aoff + m * 2048 + k * 1024); } while (0)
; #define PG8_LDB(dst, b, h) do { _Pragma("unroll") for (int n = 0; n < 2; ++n) _Pragma("unroll") for (int k = 0; k < 2; ++k) dst[n][k] = *(const LAS bf16x8*)(lds + PG8_SB(b, h) + boff + n * 2048 + k * 1024); } while (0)
; #define PG8_MMA(ai, bj, At, Bt) do { __builtin_amdgcn_s_setprio(1); _Pragma("unroll") for (int m = 0; m < 4; ++m) _Pragma("unroll") for (int n = 0; n < 2; ++n) _Pragma("unroll") for (int k = 0; k < 2; ++k) \
;         acc[ai][bj][m][n] = __builtin_amdgcn_mfma_f32_16x16x32_bf16(Bt[n][k], At[m][k], acc[ai][bj][m][n], 0, 0, 0); __builtin_amdgcn_s_setprio(0); } while (0)
; #define PG8_BAR __builtin_amdgcn_s_barrier()
; template <class Epi, class Sched>
; __device__ __forceinline__ void gemm_phase(LAS unsigned char* lds, const Gemm g, const Sched& S, const Epi& E, int tid) {
;     ...
;     for (;;) {
;         const bool has_next = S.next(ui + 1, nxt);
;         const char* nA = has_next ? (const char*)g.A + (size_t)nxt.pm * tstep : cA; const char* nB = has_next ? (const char*)g.Bt + (size_t)nxt.pn * tstep : cB;
;         for (int t = 0; t < nt; t += 2) {
;             const bool last = (t == nt - 2);
;             const char* a1 = cA + (size_t)(t + 1) * kstep;
;             const char* a2 = last ? nA : cA + (size_t)(t + 2) * kstep; const char* b2 = last ? nB : cB + (size_t)(t + 2) * kstep;
;             const char* a3 = a2 + kstep; const char* b3 = b2 + kstep;
;             PG8_LDB(B0, 0, 0); PG8_SCHED; PG8_LDA(At, 0, 0); PG8_STAGE(PG8_SA(1, 1), a1 + hstep, voffA);
;             PG8_WAIT_L(8); PG8_BAR; PG8_WAIT_L(0); PG8_MMA(0, 0, At, B0); PG8_BAR; PG8_SCHED;
;             PG8_LDB(B1, 0, 1); PG8_STAGE(PG8_SB(0, 0), b2, voffB);
;             PG8_BAR; PG8_WAIT_L(0); PG8_MMA(0, 1, At, B1); PG8_BAR;
;             PG8_LDA(At, 0, 1); PG8_STAGE(PG8_SA(0, 0), a2, voffA);
;             PG8_BAR; PG8_WAIT_L(0); PG8_MMA(1, 0, At, B0); PG8_BAR; PG8_SCHED;
.LBB0_99:
	s_add_u32 vcc_lo, s44, 0x80
	s_addc_u32 vcc_hi, s45, 0
	s_add_u32 s96, s34, 0x100
	s_addc_u32 s65, s35, 0
	s_mov_b32 s34, 0
	s_add_i32 s0, s34, 2
	s_add_u32 s1, vcc_lo, 0x80
	s_addc_u32 s35, vcc_hi, 0
	s_add_i32 s17, 0, 0x10000
	v_add_u32_e32 v152, s17, v141
	ds_read_b128 v[144:147], v152
	ds_read_b128 v[148:151], v152 offset:1024
	ds_read_b128 v[160:163], v152 offset:2048
	ds_read_b128 v[164:167], v152 offset:3072
	s_cmp_eq_u32 s95, s34
	s_cselect_b32 s34, s38, s1
	s_cselect_b32 s35, s39, s35
	s_cselect_b32 s45, s41, s65
	s_cselect_b32 s44, s40, s96
	v_lshl_add_u64 v[152:153], vcc, 0, v[134:135]
	s_add_i32 m0, s88, 0xc000
	ds_read_b128 v[168:171], v143
	ds_read_b128 v[184:187], v143 offset:1024
	ds_read_b128 v[188:191], v143 offset:2048
	ds_read_b128 v[192:195], v143 offset:3072
	ds_read_b128 v[196:199], v143 offset:4096
	ds_read_b128 v[200:203], v143 offset:5120
	ds_read_b128 v[204:207], v143 offset:6144
	ds_read_b128 v[208:211], v143 offset:7168
	global_load_lds_dwordx4 v[152:153], off
	v_lshl_add_u64 v[152:153], vcc, 0, v[136:137]
	s_add_i32 m0, s88, 0xe000
	s_nop 0
	global_load_lds_dwordx4 v[152:153], off
	s_waitcnt lgkmcnt(8)
	s_barrier
	s_waitcnt lgkmcnt(0)
	s_setprio 1
	v_mfma_f32_16x16x32_bf16 v[124:127], v[144:147], v[168:171], 0
	v_mfma_f32_16x16x32_bf16 v[120:123], v[160:163], v[168:171], 0
	v_mfma_f32_16x16x32_bf16 v[116:119], v[144:147], v[188:191], 0
	v_mfma_f32_16x16x32_bf16 v[112:115], v[160:163], v[188:191], 0
	v_mfma_f32_16x16x32_bf16 v[100:103], v[144:147], v[196:199], 0
	v_mfma_f32_16x16x32_bf16 v[96:99], v[160:163], v[196:199], 0
	v_mfma_f32_16x16x32_bf16 v[84:87], v[144:147], v[204:207], 0
	v_mfma_f32_16x16x32_bf16 v[80:83], v[160:163], v[204:207], 0
	v_mfma_f32_16x16x32_bf16 v[124:127], v[148:151], v[184:187], v[124:127]
	v_mfma_f32_16x16x32_bf16 v[120:123], v[164:167], v[184:187], v[120:123]
	v_mfma_f32_16x16x32_bf16 v[116:119], v[148:151], v[192:195], v[116:119]
	v_mfma_f32_16x16x32_bf16 v[112:115], v[164:167], v[192:195], v[112:115]
	v_mfma_f32_16x16x32_bf16 v[100:103], v[148:151], v[200:203], v[100:103]
	v_mfma_f32_16x16x32_bf16 v[96:99], v[164:167], v[200:203], v[96:99]
	v_mfma_f32_16x16x32_bf16 v[84:87], v[148:151], v[208:211], v[84:87]
	v_mfma_f32_16x16x32_bf16 v[80:83], v[164:167], v[208:211], v[80:83]
	s_setprio 0
	s_barrier
	s_add_i32 s1, 0, 0x14000
	v_add_u32_e32 v152, s1, v141
	s_add_i32 s17, s17, s85
	ds_read_b128 v[212:215], v152
	ds_read_b128 v[216:219], v152 offset:1024
	ds_read_b128 v[220:223], v152 offset:2048
	ds_read_b128 v[224:227], v152 offset:3072
	v_lshl_add_u64 v[152:153], s[44:45], 0, v[154:155]
	s_mov_b32 m0, s17
	v_lshl_add_u64 v[228:229], s[44:45], 0, v[132:133]
	global_load_lds_dwordx4 v[152:153], off
	s_add_i32 m0, s17, 0x2000
	s_nop 0
	global_load_lds_dwordx4 v[228:229], off
	s_barrier
	s_waitcnt lgkmcnt(0)
	s_setprio 1
	v_mfma_f32_16x16x32_bf16 v[108:111], v[212:215], v[168:171], 0
	v_mfma_f32_16x16x32_bf16 v[104:107], v[220:223], v[168:171], 0
	v_mfma_f32_16x16x32_bf16 v[92:95], v[212:215], v[188:191], 0
	s_mov_b32 m0, s88
	v_mfma_f32_16x16x32_bf16 v[88:91], v[220:223], v[188:191], 0
	v_lshl_add_u64 v[230:231], s[34:35], 0, v[128:129]
	v_mfma_f32_16x16x32_bf16 v[76:79], v[212:215], v[196:199], 0
	v_mfma_f32_16x16x32_bf16 v[72:75], v[220:223], v[196:199], 0
	v_mfma_f32_16x16x32_bf16 v[68:71], v[212:215], v[204:207], 0
	v_mfma_f32_16x16x32_bf16 v[64:67], v[220:223], v[204:207], 0
	v_mfma_f32_16x16x32_bf16 v[108:111], v[216:219], v[184:187], v[108:111]
	v_mfma_f32_16x16x32_bf16 v[104:107], v[224:227], v[184:187], v[104:107]
	v_mfma_f32_16x16x32_bf16 v[92:95], v[216:219], v[192:195], v[92:95]
	v_mfma_f32_16x16x32_bf16 v[88:91], v[224:227], v[192:195], v[88:91]
	v_mfma_f32_16x16x32_bf16 v[76:79], v[216:219], v[200:203], v[76:79]
	v_mfma_f32_16x16x32_bf16 v[72:75], v[224:227], v[200:203], v[72:75]
	v_mfma_f32_16x16x32_bf16 v[68:71], v[216:219], v[208:211], v[68:71]
	v_mfma_f32_16x16x32_bf16 v[64:67], v[224:227], v[208:211], v[64:67]
	s_setprio 0
	s_barrier
	ds_read_b128 v[168:171], v143 offset:16384
	ds_read_b128 v[184:187], v143 offset:17408
	ds_read_b128 v[188:191], v143 offset:18432
	ds_read_b128 v[192:195], v143 offset:19456
	ds_read_b128 v[196:199], v143 offset:20480
	ds_read_b128 v[200:203], v143 offset:21504
	ds_read_b128 v[204:207], v143 offset:22528
	ds_read_b128 v[208:211], v143 offset:23552
	global_load_lds_dwordx4 v[230:231], off
	v_lshl_add_u64 v[232:233], s[34:35], 0, v[130:131]
	s_mov_b32 m0, s89
	s_nop 0
	global_load_lds_dwordx4 v[232:233], off
	s_barrier
	s_waitcnt lgkmcnt(0)
	s_setprio 1
	v_mfma_f32_16x16x32_bf16 v[60:63], v[144:147], v[168:171], 0
	v_mfma_f32_16x16x32_bf16 v[56:59], v[160:163], v[168:171], 0
	v_mfma_f32_16x16x32_bf16 v[52:55], v[144:147], v[188:191], 0
	v_mfma_f32_16x16x32_bf16 v[48:51], v[160:163], v[188:191], 0
	v_mfma_f32_16x16x32_bf16 v[36:39], v[144:147], v[196:199], 0
	v_mfma_f32_16x16x32_bf16 v[32:35], v[160:163], v[196:199], 0
	v_mfma_f32_16x16x32_bf16 v[20:23], v[144:147], v[204:207], 0
	v_mfma_f32_16x16x32_bf16 v[16:19], v[160:163], v[204:207], 0
	v_mfma_f32_16x16x32_bf16 v[60:63], v[148:151], v[184:187], v[60:63]
	v_mfma_f32_16x16x32_bf16 v[56:59], v[164:167], v[184:187], v[56:59]
	v_mfma_f32_16x16x32_bf16 v[52:55], v[148:151], v[192:195], v[52:55]
	v_mfma_f32_16x16x32_bf16 v[48:51], v[164:167], v[192:195], v[48:51]
	v_mfma_f32_16x16x32_bf16 v[36:39], v[148:151], v[200:203], v[36:39]
	v_mfma_f32_16x16x32_bf16 v[32:35], v[164:167], v[200:203], v[32:35]
	v_mfma_f32_16x16x32_bf16 v[20:23], v[148:151], v[208:211], v[20:23]
	v_mfma_f32_16x16x32_bf16 v[16:19], v[164:167], v[208:211], v[16:19]
	s_setprio 0
	s_barrier
; #define PG8_STAGE(bufoff, gbase, voff) do { _Pragma("unroll") for (int _i = 0; _i < 2; ++_i) \
;         __builtin_amdgcn_global_load_lds((const unsigned*)((const char*)(gbase) + (voff)[_i]), (LAS unsigned*)(lds + (bufoff) + ldsw + _i * 8192), 16, 0, 0); } while (0)
; #define PG8_LDA(dst, b, h) do { _Pragma("unroll") for (int m = 0; m < 4; ++m) _Pragma("unroll") for (int k = 0; k < 2; ++k) dst[m][k] = *(const LAS bf16x8*)(lds + PG8_SA(b, h) + aoff + m * 2048 + k * 1024); } while (0)
; #define PG8_LDB(dst, b, h) do { _Pragma("unroll") for (int n = 0; n < 2; ++n) _Pragma("unroll") for (int k = 0; k < 2; ++k) dst[n][k] = *(const LAS bf16x8*)(lds + PG8_SB(b, h) + boff + n * 2048 + k * 1024); } while (0)
; #define PG8_MMA(ai, bj, At, Bt) do { __builtin_amdgcn_s_setprio(1); _Pragma("unroll") for (int m = 0; m < 4; ++m) _Pragma("unroll") for (int n = 0; n < 2; ++n) _Pragma("unroll") for (int k = 0; k < 2; ++k) \
;         acc[ai][bj][m][n] = __builtin_amdgcn_mfma_f32_16x16x32_bf16(Bt[n][k], At[m][k], acc[ai][bj][m][n], 0, 0, 0); __builtin_amdgcn_s_setprio(0); } while (0)
; #define PG8_WAIT_V(n) asm volatile("s_waitcnt vmcnt(" #n ")" ::: "memory")
; #define PG8_WAIT_L(n) asm volatile("s_waitcnt lgkmcnt(" #n ")" ::: "memory")
; #define PG8_BAR __builtin_amdgcn_s_barrier()
; #define PG8_SCHED __builtin_amdgcn_sched_barrier(0)
; template <class Epi, class Sched>
; __device__ __forceinline__ void gemm_phase(LAS unsigned char* lds, const Gemm g, const Sched& S, const Epi& E, int tid) {
;     ...
;             PG8_BAR; PG8_WAIT_L(0); PG8_MMA(1, 0, At, B0); PG8_BAR; PG8_SCHED;
;             PG8_STAGE(PG8_SB(0, 1), b2 + hstep, voffB);
;             PG8_WAIT_V(6); PG8_BAR; PG8_MMA(1, 1, At, B1); PG8_BAR;
;             PG8_LDB(B0, 1, 0); PG8_SCHED; PG8_LDA(At, 1, 0); PG8_STAGE(PG8_SA(0, 1), a2 + hstep, voffA);
;             PG8_WAIT_L(8); PG8_BAR; PG8_WAIT_L(0); PG8_MMA(0, 0, At, B0); PG8_BAR; PG8_SCHED;
;             PG8_LDB(B1, 1, 1); PG8_STAGE(PG8_SB(1, 0), b3, voffB);
;             PG8_BAR; PG8_WAIT_L(0); PG8_MMA(0, 1, At, B1); PG8_BAR;
;             PG8_LDA(At, 1, 1); PG8_STAGE(PG8_SA(1, 0), a3, voffA);
;             PG8_BAR; PG8_WAIT_L(0); PG8_MMA(1, 0, At, B0); PG8_BAR; PG8_SCHED;
	s_add_u32 s44, s44, s6
	s_addc_u32 s45, s45, 0
	s_add_i32 s1, s1, s85
	v_lshl_add_u64 v[234:235], s[44:45], 0, v[154:155]
	s_mov_b32 m0, s1
	v_lshl_add_u64 v[236:237], s[44:45], 0, v[132:133]
	global_load_lds_dwordx4 v[234:235], off
	s_add_i32 m0, s1, 0x2000
	s_nop 0
	global_load_lds_dwordx4 v[236:237], off
	s_waitcnt vmcnt(24)
	s_barrier
	s_setprio 1
	v_mfma_f32_16x16x32_bf16 v[44:47], v[212:215], v[168:171], 0
	v_mfma_f32_16x16x32_bf16 v[40:43], v[220:223], v[168:171], 0
	v_mfma_f32_16x16x32_bf16 v[28:31], v[212:215], v[188:191], 0
	s_add_i32 s1, 0, 0x18000
	v_mfma_f32_16x16x32_bf16 v[24:27], v[220:223], v[188:191], 0
	v_add_u32_e32 v164, s1, v141
	v_mfma_f32_16x16x32_bf16 v[12:15], v[212:215], v[196:199], 0
	v_mfma_f32_16x16x32_bf16 v[8:11], v[220:223], v[196:199], 0
	v_mfma_f32_16x16x32_bf16 v[4:7], v[212:215], v[204:207], 0
	v_mfma_f32_16x16x32_bf16 v[0:3], v[220:223], v[204:207], 0
	v_mfma_f32_16x16x32_bf16 v[44:47], v[216:219], v[184:187], v[44:47]
	v_mfma_f32_16x16x32_bf16 v[40:43], v[224:227], v[184:187], v[40:43]
	v_mfma_f32_16x16x32_bf16 v[28:31], v[216:219], v[192:195], v[28:31]
	v_mfma_f32_16x16x32_bf16 v[24:27], v[224:227], v[192:195], v[24:27]
	v_mfma_f32_16x16x32_bf16 v[12:15], v[216:219], v[200:203], v[12:15]
	v_mfma_f32_16x16x32_bf16 v[8:11], v[224:227], v[200:203], v[8:11]
	v_mfma_f32_16x16x32_bf16 v[4:7], v[216:219], v[208:211], v[4:7]
	v_mfma_f32_16x16x32_bf16 v[0:3], v[224:227], v[208:211], v[0:3]
	s_setprio 0
	s_barrier
	ds_read_b128 v[144:147], v164
	ds_read_b128 v[148:151], v164 offset:1024
	ds_read_b128 v[160:163], v164 offset:2048
	ds_read_b128 v[164:167], v164 offset:3072
	s_add_u32 s34, s34, s6
	s_addc_u32 s35, s35, 0
	s_mov_b32 m0, s90
	v_lshl_add_u64 v[212:213], s[34:35], 0, v[128:129]
	ds_read_b128 v[168:171], v143 offset:32768
	ds_read_b128 v[184:187], v143 offset:33792
	ds_read_b128 v[188:191], v143 offset:34816
	ds_read_b128 v[192:195], v143 offset:35840
	ds_read_b128 v[196:199], v143 offset:36864
	ds_read_b128 v[200:203], v143 offset:37888
	ds_read_b128 v[204:207], v143 offset:38912
	ds_read_b128 v[208:211], v143 offset:39936
	global_load_lds_dwordx4 v[212:213], off
	v_lshl_add_u64 v[212:213], s[34:35], 0, v[130:131]
	s_mov_b32 m0, s91
	s_nop 0
	global_load_lds_dwordx4 v[212:213], off
	s_waitcnt lgkmcnt(8)
	s_barrier
	s_waitcnt lgkmcnt(0)
	s_setprio 1
	v_mfma_f32_16x16x32_bf16 v[124:127], v[144:147], v[168:171], v[124:127]
	v_mfma_f32_16x16x32_bf16 v[120:123], v[160:163], v[168:171], v[120:123]
	v_mfma_f32_16x16x32_bf16 v[116:119], v[144:147], v[188:191], v[116:119]
	v_mfma_f32_16x16x32_bf16 v[112:115], v[160:163], v[188:191], v[112:115]
	v_mfma_f32_16x16x32_bf16 v[100:103], v[144:147], v[196:199], v[100:103]
	v_mfma_f32_16x16x32_bf16 v[96:99], v[160:163], v[196:199], v[96:99]
	v_mfma_f32_16x16x32_bf16 v[84:87], v[144:147], v[204:207], v[84:87]
	v_mfma_f32_16x16x32_bf16 v[80:83], v[160:163], v[204:207], v[80:83]
	v_mfma_f32_16x16x32_bf16 v[124:127], v[148:151], v[184:187], v[124:127]
	v_mfma_f32_16x16x32_bf16 v[120:123], v[164:167], v[184:187], v[120:123]
	v_mfma_f32_16x16x32_bf16 v[116:119], v[148:151], v[192:195], v[116:119]
	v_mfma_f32_16x16x32_bf16 v[112:115], v[164:167], v[192:195], v[112:115]
	v_mfma_f32_16x16x32_bf16 v[100:103], v[148:151], v[200:203], v[100:103]
	v_mfma_f32_16x16x32_bf16 v[96:99], v[164:167], v[200:203], v[96:99]
	v_mfma_f32_16x16x32_bf16 v[84:87], v[148:151], v[208:211], v[84:87]
	v_mfma_f32_16x16x32_bf16 v[80:83], v[164:167], v[208:211], v[80:83]
	s_setprio 0
	s_barrier
	s_add_i32 s17, 0, 0x1c000
	s_add_i32 s1, s1, s85
	v_add_u32_e32 v183, s17, v141
	v_lshl_add_u64 v[152:153], v[152:153], 0, s[8:9]
	s_mov_b32 m0, s1
	ds_read_b128 v[212:215], v183
	ds_read_b128 v[216:219], v183 offset:1024
	ds_read_b128 v[220:223], v183 offset:2048
	ds_read_b128 v[224:227], v183 offset:3072
	global_load_lds_dwordx4 v[152:153], off
	v_lshl_add_u64 v[152:153], v[228:229], 0, s[8:9]
	s_add_i32 m0, s1, 0x2000
	s_nop 0
	global_load_lds_dwordx4 v[152:153], off
	s_waitcnt vmcnt(10)
	s_barrier
	s_waitcnt lgkmcnt(0)
	s_setprio 1
	v_mfma_f32_16x16x32_bf16 v[108:111], v[212:215], v[168:171], v[108:111]
	v_mfma_f32_16x16x32_bf16 v[104:107], v[220:223], v[168:171], v[104:107]
	v_mfma_f32_16x16x32_bf16 v[92:95], v[212:215], v[188:191], v[92:95]
	s_mov_b32 m0, s92
	v_mfma_f32_16x16x32_bf16 v[88:91], v[220:223], v[188:191], v[88:91]
	v_lshl_add_u64 v[152:153], v[230:231], 0, s[8:9]
	v_mfma_f32_16x16x32_bf16 v[76:79], v[212:215], v[196:199], v[76:79]
	v_mfma_f32_16x16x32_bf16 v[72:75], v[220:223], v[196:199], v[72:75]
	v_mfma_f32_16x16x32_bf16 v[68:71], v[212:215], v[204:207], v[68:71]
	v_mfma_f32_16x16x32_bf16 v[64:67], v[220:223], v[204:207], v[64:67]
	v_mfma_f32_16x16x32_bf16 v[108:111], v[216:219], v[184:187], v[108:111]
	v_mfma_f32_16x16x32_bf16 v[104:107], v[224:227], v[184:187], v[104:107]
	v_mfma_f32_16x16x32_bf16 v[92:95], v[216:219], v[192:195], v[92:95]
	v_mfma_f32_16x16x32_bf16 v[88:91], v[224:227], v[192:195], v[88:91]
	v_mfma_f32_16x16x32_bf16 v[76:79], v[216:219], v[200:203], v[76:79]
	v_mfma_f32_16x16x32_bf16 v[72:75], v[224:227], v[200:203], v[72:75]
	v_mfma_f32_16x16x32_bf16 v[68:71], v[216:219], v[208:211], v[68:71]
	v_mfma_f32_16x16x32_bf16 v[64:67], v[224:227], v[208:211], v[64:67]
	s_setprio 0
	s_barrier
	ds_read_b128 v[168:171], v143 offset:49152
	ds_read_b128 v[184:187], v143 offset:50176
	ds_read_b128 v[188:191], v143 offset:51200
	ds_read_b128 v[192:195], v143 offset:52224
	ds_read_b128 v[196:199], v143 offset:53248
	ds_read_b128 v[200:203], v143 offset:54272
	ds_read_b128 v[204:207], v143 offset:55296
	ds_read_b128 v[208:211], v143 offset:56320
	global_load_lds_dwordx4 v[152:153], off
	v_lshl_add_u64 v[152:153], v[232:233], 0, s[8:9]
	s_mov_b32 m0, s93
	s_nop 0
	global_load_lds_dwordx4 v[152:153], off
	s_barrier
; #define PG8_STAGE(bufoff, gbase, voff) do { _Pragma("unroll") for (int _i = 0; _i < 2; ++_i) \
;         __builtin_amdgcn_global_load_lds((const unsigned*)((const char*)(gbase) + (voff)[_i]), (LAS unsigned*)(lds + (bufoff) + ldsw + _i * 8192), 16, 0, 0); } while (0)
; #define PG8_LDA(dst, b, h) do { _Pragma("unroll") for (int m = 0; m < 4; ++m) _Pragma("unroll") for (int k = 0; k < 2; ++k) dst[m][k] = *(const LAS bf16x8*)(lds + PG8_SA(b, h) + aoff + m * 2048 + k * 1024); } while (0)
; #define PG8_LDB(dst, b, h) do { _Pragma("unroll") for (int n = 0; n < 2; ++n) _Pragma("unroll") for (int k = 0; k < 2; ++k) dst[n][k] = *(const LAS bf16x8*)(lds + PG8_SB(b, h) + boff + n * 2048 + k * 1024); } while (0)
; #define PG8_MMA(ai, bj, At, Bt) do { __builtin_amdgcn_s_setprio(1); _Pragma("unroll") for (int m = 0; m < 4; ++m) _Pragma("unroll") for (int n = 0; n < 2; ++n) _Pragma("unroll") for (int k = 0; k < 2; ++k) \
;         acc[ai][bj][m][n] = __builtin_amdgcn_mfma_f32_16x16x32_bf16(Bt[n][k], At[m][k], acc[ai][bj][m][n], 0, 0, 0); __builtin_amdgcn_s_setprio(0); } while (0)
; #define PG8_WAIT_V(n) asm volatile("s_waitcnt vmcnt(" #n ")" ::: "memory")
; #define PG8_WAIT_L(n) asm volatile("s_waitcnt lgkmcnt(" #n ")" ::: "memory")
; #define PG8_BAR __builtin_amdgcn_s_barrier()
; #define PG8_SCHED __builtin_amdgcn_sched_barrier(0)
; template <class Epi, class Sched>
; __device__ __forceinline__ void gemm_phase(LAS unsigned char* lds, const Gemm g, const Sched& S, const Epi& E, int tid) {
;     ...
;             const bool last = (t == nt - 2);
;             const char* a1 = cA + (size_t)(t + 1) * kstep;
;             const char* a2 = last ? nA : cA + (size_t)(t + 2) * kstep; const char* b2 = last ? nB : cB + (size_t)(t + 2) * kstep;
;             const char* a3 = a2 + kstep; const char* b3 = b2 + kstep;
;             PG8_LDB(B0, 0, 0); PG8_SCHED; PG8_LDA(At, 0, 0); PG8_STAGE(PG8_SA(1, 1), a1 + hstep, voffA);
;             PG8_WAIT_L(8); PG8_BAR; PG8_WAIT_L(0); PG8_MMA(0, 0, At, B0); PG8_BAR; PG8_SCHED;
;             PG8_LDB(B1, 0, 1); PG8_STAGE(PG8_SB(0, 0), b2, voffB);
;             PG8_BAR; PG8_WAIT_L(0); PG8_MMA(0, 1, At, B1); PG8_BAR;
;     ...
;             PG8_BAR; PG8_WAIT_L(0); PG8_MMA(1, 0, At, B0); PG8_BAR; PG8_SCHED;
;             PG8_STAGE(PG8_SB(1, 1), b3 + hstep, voffB);
;             PG8_WAIT_V(6); PG8_BAR; PG8_MMA(1, 1, At, B1); PG8_BAR;
	s_waitcnt lgkmcnt(0)
	s_setprio 1
	v_mfma_f32_16x16x32_bf16 v[60:63], v[144:147], v[168:171], v[60:63]
	v_mfma_f32_16x16x32_bf16 v[56:59], v[160:163], v[168:171], v[56:59]
	v_mfma_f32_16x16x32_bf16 v[52:55], v[144:147], v[188:191], v[52:55]
	v_mfma_f32_16x16x32_bf16 v[48:51], v[160:163], v[188:191], v[48:51]
	v_mfma_f32_16x16x32_bf16 v[36:39], v[144:147], v[196:199], v[36:39]
	v_mfma_f32_16x16x32_bf16 v[32:35], v[160:163], v[196:199], v[32:35]
	v_mfma_f32_16x16x32_bf16 v[20:23], v[144:147], v[204:207], v[20:23]
	v_mfma_f32_16x16x32_bf16 v[16:19], v[160:163], v[204:207], v[16:19]
	v_mfma_f32_16x16x32_bf16 v[60:63], v[148:151], v[184:187], v[60:63]
	v_mfma_f32_16x16x32_bf16 v[56:59], v[164:167], v[184:187], v[56:59]
	v_mfma_f32_16x16x32_bf16 v[52:55], v[148:151], v[192:195], v[52:55]
	v_mfma_f32_16x16x32_bf16 v[48:51], v[164:167], v[192:195], v[48:51]
	v_mfma_f32_16x16x32_bf16 v[36:39], v[148:151], v[200:203], v[36:39]
	v_mfma_f32_16x16x32_bf16 v[32:35], v[164:167], v[200:203], v[32:35]
	v_mfma_f32_16x16x32_bf16 v[20:23], v[148:151], v[208:211], v[20:23]
	v_mfma_f32_16x16x32_bf16 v[16:19], v[164:167], v[208:211], v[16:19]
	s_setprio 0
	s_barrier
	s_add_i32 s1, s17, s85
	v_lshl_add_u64 v[144:145], v[234:235], 0, s[8:9]
	s_mov_b32 m0, s1
	s_nop 0
	global_load_lds_dwordx4 v[144:145], off
	v_lshl_add_u64 v[144:145], v[236:237], 0, s[8:9]
	s_add_i32 m0, s1, 0x2000
	s_nop 0
	global_load_lds_dwordx4 v[144:145], off
	s_waitcnt vmcnt(6)
	s_barrier
	s_setprio 1
	v_mfma_f32_16x16x32_bf16 v[44:47], v[212:215], v[168:171], v[44:47]
	v_mfma_f32_16x16x32_bf16 v[40:43], v[220:223], v[168:171], v[40:43]
	v_mfma_f32_16x16x32_bf16 v[28:31], v[212:215], v[188:191], v[28:31]
	s_add_u32 vcc_lo, vcc_lo, 0x100
	v_mfma_f32_16x16x32_bf16 v[24:27], v[220:223], v[188:191], v[24:27]
	s_addc_u32 vcc_hi, vcc_hi, 0
	v_mfma_f32_16x16x32_bf16 v[12:15], v[212:215], v[196:199], v[12:15]
	s_add_u32 s96, s96, 0x100
	v_mfma_f32_16x16x32_bf16 v[8:11], v[220:223], v[196:199], v[8:11]
	s_addc_u32 s65, s65, 0
	v_mfma_f32_16x16x32_bf16 v[4:7], v[212:215], v[204:207], v[4:7]
	s_cmp_ge_u32 s0, s94
	v_mfma_f32_16x16x32_bf16 v[0:3], v[220:223], v[204:207], v[0:3]
	s_mov_b32 s34, s0
	v_mfma_f32_16x16x32_bf16 v[44:47], v[216:219], v[184:187], v[44:47]
	v_mfma_f32_16x16x32_bf16 v[40:43], v[224:227], v[184:187], v[40:43]
	v_mfma_f32_16x16x32_bf16 v[28:31], v[216:219], v[192:195], v[28:31]
	v_mfma_f32_16x16x32_bf16 v[24:27], v[224:227], v[192:195], v[24:27]
	v_mfma_f32_16x16x32_bf16 v[12:15], v[216:219], v[200:203], v[12:15]
	v_mfma_f32_16x16x32_bf16 v[8:11], v[224:227], v[200:203], v[8:11]
	v_mfma_f32_16x16x32_bf16 v[4:7], v[216:219], v[208:211], v[4:7]
	v_mfma_f32_16x16x32_bf16 v[0:3], v[224:227], v[208:211], v[0:3]
	s_setprio 0
	s_barrier
	s_cbranch_scc1 .Lpeel_exit_plain
.LBB0_100:
	s_add_i32 s0, s34, 2
	s_add_u32 s1, vcc_lo, 0x80
	s_addc_u32 s35, vcc_hi, 0
	s_add_i32 s17, 0, 0x10000
	v_add_u32_e32 v152, s17, v141
	ds_read_b128 v[144:147], v152
	ds_read_b128 v[148:151], v152 offset:1024
	ds_read_b128 v[160:163], v152 offset:2048
	ds_read_b128 v[164:167], v152 offset:3072
	s_cmp_eq_u32 s95, s34
	s_cselect_b32 s34, s38, s1
	s_cselect_b32 s35, s39, s35
	s_cselect_b32 s45, s41, s65
	s_cselect_b32 s44, s40, s96
	v_lshl_add_u64 v[152:153], vcc, 0, v[134:135]
	s_add_i32 m0, s88, 0xc000
	ds_read_b128 v[168:171], v143
	ds_read_b128 v[184:187], v143 offset:1024
	ds_read_b128 v[188:191], v143 offset:2048
	ds_read_b128 v[192:195], v143 offset:3072
	ds_read_b128 v[196:199], v143 offset:4096
	ds_read_b128 v[200:203], v143 offset:5120
	ds_read_b128 v[204:207], v143 offset:6144
	ds_read_b128 v[208:211], v143 offset:7168
	global_load_lds_dwordx4 v[152:153], off
	v_lshl_add_u64 v[152:153], vcc, 0, v[136:137]
	s_add_i32 m0, s88, 0xe000
	s_nop 0
	global_load_lds_dwordx4 v[152:153], off
	s_waitcnt lgkmcnt(8)
	s_barrier
	s_waitcnt lgkmcnt(0)
	s_setprio 1
	v_mfma_f32_16x16x32_bf16 v[124:127], v[144:147], v[168:171], v[124:127]
	v_mfma_f32_16x16x32_bf16 v[120:123], v[160:163], v[168:171], v[120:123]
	v_mfma_f32_16x16x32_bf16 v[116:119], v[144:147], v[188:191], v[116:119]
	v_mfma_f32_16x16x32_bf16 v[112:115], v[160:163], v[188:191], v[112:115]
	v_mfma_f32_16x16x32_bf16 v[100:103], v[144:147], v[196:199], v[100:103]
	v_mfma_f32_16x16x32_bf16 v[96:99], v[160:163], v[196:199], v[96:99]
	v_mfma_f32_16x16x32_bf16 v[84:87], v[144:147], v[204:207], v[84:87]
	v_mfma_f32_16x16x32_bf16 v[80:83], v[160:163], v[204:207], v[80:83]
	v_mfma_f32_16x16x32_bf16 v[124:127], v[148:151], v[184:187], v[124:127]
	v_mfma_f32_16x16x32_bf16 v[120:123], v[164:167], v[184:187], v[120:123]
	v_mfma_f32_16x16x32_bf16 v[116:119], v[148:151], v[192:195], v[116:119]
	v_mfma_f32_16x16x32_bf16 v[112:115], v[164:167], v[192:195], v[112:115]
	v_mfma_f32_16x16x32_bf16 v[100:103], v[148:151], v[200:203], v[100:103]
	v_mfma_f32_16x16x32_bf16 v[96:99], v[164:167], v[200:203], v[96:99]
	v_mfma_f32_16x16x32_bf16 v[84:87], v[148:151], v[208:211], v[84:87]
	v_mfma_f32_16x16x32_bf16 v[80:83], v[164:167], v[208:211], v[80:83]
	s_setprio 0
	s_barrier
	s_add_i32 s1, 0, 0x14000
	v_add_u32_e32 v152, s1, v141
	s_add_i32 s17, s17, s85
	ds_read_b128 v[212:215], v152
	ds_read_b128 v[216:219], v152 offset:1024
	ds_read_b128 v[220:223], v152 offset:2048
	ds_read_b128 v[224:227], v152 offset:3072
	v_lshl_add_u64 v[152:153], s[44:45], 0, v[154:155]
	s_mov_b32 m0, s17
	v_lshl_add_u64 v[228:229], s[44:45], 0, v[132:133]
	global_load_lds_dwordx4 v[152:153], off
	s_add_i32 m0, s17, 0x2000
	s_nop 0
	global_load_lds_dwordx4 v[228:229], off
	s_barrier
; #define PG8_STAGE(bufoff, gbase, voff) do { _Pragma("unroll") for (int _i = 0; _i < 2; ++_i) \
;         __builtin_amdgcn_global_load_lds((const unsigned*)((const char*)(gbase) + (voff)[_i]), (LAS unsigned*)(lds + (bufoff) + ldsw + _i * 8192), 16, 0, 0); } while (0)
; #define PG8_LDA(dst, b, h) do { _Pragma("unroll") for (int m = 0; m < 4; ++m) _Pragma("unroll") for (int k = 0; k < 2; ++k) dst[m][k] = *(const LAS bf16x8*)(lds + PG8_SA(b, h) + aoff + m * 2048 + k * 1024); } while (0)
; #define PG8_LDB(dst, b, h) do { _Pragma("unroll") for (int n = 0; n < 2; ++n) _Pragma("unroll") for (int k = 0; k < 2; ++k) dst[n][k] = *(const LAS bf16x8*)(lds + PG8_SB(b, h) + boff + n * 2048 + k * 1024); } while (0)
; #define PG8_MMA(ai, bj, At, Bt) do { __builtin_amdgcn_s_setprio(1); _Pragma("unroll") for (int m = 0; m < 4; ++m) _Pragma("unroll") for (int n = 0; n < 2; ++n) _Pragma("unroll") for (int k = 0; k < 2; ++k) \
;         acc[ai][bj][m][n] = __builtin_amdgcn_mfma_f32_16x16x32_bf16(Bt[n][k], At[m][k], acc[ai][bj][m][n], 0, 0, 0); __builtin_amdgcn_s_setprio(0); } while (0)
; #define PG8_WAIT_V(n) asm volatile("s_waitcnt vmcnt(" #n ")" ::: "memory")
; #define PG8_WAIT_L(n) asm volatile("s_waitcnt lgkmcnt(" #n ")" ::: "memory")
; #define PG8_BAR __builtin_amdgcn_s_barrier()
; #define PG8_SCHED __builtin_amdgcn_sched_barrier(0)
; template <class Epi, class Sched>
; __device__ __forceinline__ void gemm_phase(LAS unsigned char* lds, const Gemm g, const Sched& S, const Epi& E, int tid) {
;     ...
;             PG8_BAR; PG8_WAIT_L(0); PG8_MMA(0, 1, At, B1); PG8_BAR;
;             PG8_LDA(At, 0, 1); PG8_STAGE(PG8_SA(0, 0), a2, voffA);
;             PG8_BAR; PG8_WAIT_L(0); PG8_MMA(1, 0, At, B0); PG8_BAR; PG8_SCHED;
;             PG8_STAGE(PG8_SB(0, 1), b2 + hstep, voffB);
;             PG8_WAIT_V(6); PG8_BAR; PG8_MMA(1, 1, At, B1); PG8_BAR;
;             PG8_LDB(B0, 1, 0); PG8_SCHED; PG8_LDA(At, 1, 0); PG8_STAGE(PG8_SA(0, 1), a2 + hstep, voffA);
	s_waitcnt lgkmcnt(0)
	s_setprio 1
	v_mfma_f32_16x16x32_bf16 v[108:111], v[212:215], v[168:171], v[108:111]
	v_mfma_f32_16x16x32_bf16 v[104:107], v[220:223], v[168:171], v[104:107]
	v_mfma_f32_16x16x32_bf16 v[92:95], v[212:215], v[188:191], v[92:95]
	s_mov_b32 m0, s88
	v_mfma_f32_16x16x32_bf16 v[88:91], v[220:223], v[188:191], v[88:91]
	v_lshl_add_u64 v[230:231], s[34:35], 0, v[128:129]
	v_mfma_f32_16x16x32_bf16 v[76:79], v[212:215], v[196:199], v[76:79]
	v_mfma_f32_16x16x32_bf16 v[72:75], v[220:223], v[196:199], v[72:75]
	v_mfma_f32_16x16x32_bf16 v[68:71], v[212:215], v[204:207], v[68:71]
	v_mfma_f32_16x16x32_bf16 v[64:67], v[220:223], v[204:207], v[64:67]
	v_mfma_f32_16x16x32_bf16 v[108:111], v[216:219], v[184:187], v[108:111]
	v_mfma_f32_16x16x32_bf16 v[104:107], v[224:227], v[184:187], v[104:107]
	v_mfma_f32_16x16x32_bf16 v[92:95], v[216:219], v[192:195], v[92:95]
	v_mfma_f32_16x16x32_bf16 v[88:91], v[224:227], v[192:195], v[88:91]
	v_mfma_f32_16x16x32_bf16 v[76:79], v[216:219], v[200:203], v[76:79]
	v_mfma_f32_16x16x32_bf16 v[72:75], v[224:227], v[200:203], v[72:75]
	v_mfma_f32_16x16x32_bf16 v[68:71], v[216:219], v[208:211], v[68:71]
	v_mfma_f32_16x16x32_bf16 v[64:67], v[224:227], v[208:211], v[64:67]
	s_setprio 0
	s_barrier
	ds_read_b128 v[168:171], v143 offset:16384
	ds_read_b128 v[184:187], v143 offset:17408
	ds_read_b128 v[188:191], v143 offset:18432
	ds_read_b128 v[192:195], v143 offset:19456
	ds_read_b128 v[196:199], v143 offset:20480
	ds_read_b128 v[200:203], v143 offset:21504
	ds_read_b128 v[204:207], v143 offset:22528
	ds_read_b128 v[208:211], v143 offset:23552
	global_load_lds_dwordx4 v[230:231], off
	v_lshl_add_u64 v[232:233], s[34:35], 0, v[130:131]
	s_mov_b32 m0, s89
	s_nop 0
	global_load_lds_dwordx4 v[232:233], off
	s_barrier
	s_waitcnt lgkmcnt(0)
	s_setprio 1
	v_mfma_f32_16x16x32_bf16 v[60:63], v[144:147], v[168:171], v[60:63]
	v_mfma_f32_16x16x32_bf16 v[56:59], v[160:163], v[168:171], v[56:59]
	v_mfma_f32_16x16x32_bf16 v[52:55], v[144:147], v[188:191], v[52:55]
	v_mfma_f32_16x16x32_bf16 v[48:51], v[160:163], v[188:191], v[48:51]
	v_mfma_f32_16x16x32_bf16 v[36:39], v[144:147], v[196:199], v[36:39]
	v_mfma_f32_16x16x32_bf16 v[32:35], v[160:163], v[196:199], v[32:35]
	v_mfma_f32_16x16x32_bf16 v[20:23], v[144:147], v[204:207], v[20:23]
	v_mfma_f32_16x16x32_bf16 v[16:19], v[160:163], v[204:207], v[16:19]
	v_mfma_f32_16x16x32_bf16 v[60:63], v[148:151], v[184:187], v[60:63]
	v_mfma_f32_16x16x32_bf16 v[56:59], v[164:167], v[184:187], v[56:59]
	v_mfma_f32_16x16x32_bf16 v[52:55], v[148:151], v[192:195], v[52:55]
	v_mfma_f32_16x16x32_bf16 v[48:51], v[164:167], v[192:195], v[48:51]
	v_mfma_f32_16x16x32_bf16 v[36:39], v[148:151], v[200:203], v[36:39]
	v_mfma_f32_16x16x32_bf16 v[32:35], v[164:167], v[200:203], v[32:35]
	v_mfma_f32_16x16x32_bf16 v[20:23], v[148:151], v[208:211], v[20:23]
	v_mfma_f32_16x16x32_bf16 v[16:19], v[164:167], v[208:211], v[16:19]
	s_setprio 0
	s_barrier
	s_add_u32 s44, s44, s6
	s_addc_u32 s45, s45, 0
	s_add_i32 s1, s1, s85
	v_lshl_add_u64 v[234:235], s[44:45], 0, v[154:155]
	s_mov_b32 m0, s1
	v_lshl_add_u64 v[236:237], s[44:45], 0, v[132:133]
	global_load_lds_dwordx4 v[234:235], off
	s_add_i32 m0, s1, 0x2000
	s_nop 0
	global_load_lds_dwordx4 v[236:237], off
	s_waitcnt vmcnt(6)
	s_barrier
	s_setprio 1
	v_mfma_f32_16x16x32_bf16 v[44:47], v[212:215], v[168:171], v[44:47]
	v_mfma_f32_16x16x32_bf16 v[40:43], v[220:223], v[168:171], v[40:43]
	v_mfma_f32_16x16x32_bf16 v[28:31], v[212:215], v[188:191], v[28:31]
	s_add_i32 s1, 0, 0x18000
	v_mfma_f32_16x16x32_bf16 v[24:27], v[220:223], v[188:191], v[24:27]
	v_add_u32_e32 v164, s1, v141
	v_mfma_f32_16x16x32_bf16 v[12:15], v[212:215], v[196:199], v[12:15]
	v_mfma_f32_16x16x32_bf16 v[8:11], v[220:223], v[196:199], v[8:11]
	v_mfma_f32_16x16x32_bf16 v[4:7], v[212:215], v[204:207], v[4:7]
	v_mfma_f32_16x16x32_bf16 v[0:3], v[220:223], v[204:207], v[0:3]
	v_mfma_f32_16x16x32_bf16 v[44:47], v[216:219], v[184:187], v[44:47]
	v_mfma_f32_16x16x32_bf16 v[40:43], v[224:227], v[184:187], v[40:43]
	v_mfma_f32_16x16x32_bf16 v[28:31], v[216:219], v[192:195], v[28:31]
	v_mfma_f32_16x16x32_bf16 v[24:27], v[224:227], v[192:195], v[24:27]
	v_mfma_f32_16x16x32_bf16 v[12:15], v[216:219], v[200:203], v[12:15]
	v_mfma_f32_16x16x32_bf16 v[8:11], v[224:227], v[200:203], v[8:11]
	v_mfma_f32_16x16x32_bf16 v[4:7], v[216:219], v[208:211], v[4:7]
	v_mfma_f32_16x16x32_bf16 v[0:3], v[224:227], v[208:211], v[0:3]
	s_setprio 0
	s_barrier
	ds_read_b128 v[144:147], v164
	ds_read_b128 v[148:151], v164 offset:1024
	ds_read_b128 v[160:163], v164 offset:2048
	ds_read_b128 v[164:167], v164 offset:3072
	s_add_u32 s34, s34, s6
	s_addc_u32 s35, s35, 0
	s_mov_b32 m0, s90
	v_lshl_add_u64 v[212:213], s[34:35], 0, v[128:129]
	ds_read_b128 v[168:171], v143 offset:32768
	ds_read_b128 v[184:187], v143 offset:33792
	ds_read_b128 v[188:191], v143 offset:34816
	ds_read_b128 v[192:195], v143 offset:35840
	ds_read_b128 v[196:199], v143 offset:36864
	ds_read_b128 v[200:203], v143 offset:37888
	ds_read_b128 v[204:207], v143 offset:38912
	ds_read_b128 v[208:211], v143 offset:39936
	global_load_lds_dwordx4 v[212:213], off
	v_lshl_add_u64 v[212:213], s[34:35], 0, v[130:131]
	s_mov_b32 m0, s91
	s_nop 0
	global_load_lds_dwordx4 v[212:213], off
	s_waitcnt lgkmcnt(8)
	s_barrier
; #define PG8_STAGE(bufoff, gbase, voff) do { _Pragma("unroll") for (int _i = 0; _i < 2; ++_i) \
;         __builtin_amdgcn_global_load_lds((const unsigned*)((const char*)(gbase) + (voff)[_i]), (LAS unsigned*)(lds + (bufoff) + ldsw + _i * 8192), 16, 0, 0); } while (0)
; #define PG8_LDA(dst, b, h) do { _Pragma("unroll") for (int m = 0; m < 4; ++m) _Pragma("unroll") for (int k = 0; k < 2; ++k) dst[m][k] = *(const LAS bf16x8*)(lds + PG8_SA(b, h) + aoff + m * 2048 + k * 1024); } while (0)
; #define PG8_LDB(dst, b, h) do { _Pragma("unroll") for (int n = 0; n < 2; ++n) _Pragma("unroll") for (int k = 0; k < 2; ++k) dst[n][k] = *(const LAS bf16x8*)(lds + PG8_SB(b, h) + boff + n * 2048 + k * 1024); } while (0)
; #define PG8_MMA(ai, bj, At, Bt) do { __builtin_amdgcn_s_setprio(1); _Pragma("unroll") for (int m = 0; m < 4; ++m) _Pragma("unroll") for (int n = 0; n < 2; ++n) _Pragma("unroll") for (int k = 0; k < 2; ++k) \
;         acc[ai][bj][m][n] = __builtin_amdgcn_mfma_f32_16x16x32_bf16(Bt[n][k], At[m][k], acc[ai][bj][m][n], 0, 0, 0); __builtin_amdgcn_s_setprio(0); } while (0)
; #define PG8_WAIT_V(n) asm volatile("s_waitcnt vmcnt(" #n ")" ::: "memory")
; #define PG8_WAIT_L(n) asm volatile("s_waitcnt lgkmcnt(" #n ")" ::: "memory")
; #define PG8_BAR __builtin_amdgcn_s_barrier()
; #define PG8_SCHED __builtin_amdgcn_sched_barrier(0)
; template <class Epi, class Sched>
; __device__ __forceinline__ void gemm_phase(LAS unsigned char* lds, const Gemm g, const Sched& S, const Epi& E, int tid) {
;     ...
;             PG8_WAIT_L(8); PG8_BAR; PG8_WAIT_L(0); PG8_MMA(0, 0, At, B0); PG8_BAR; PG8_SCHED;
;             PG8_LDB(B1, 1, 1); PG8_STAGE(PG8_SB(1, 0), b3, voffB);
;             PG8_BAR; PG8_WAIT_L(0); PG8_MMA(0, 1, At, B1); PG8_BAR;
;             PG8_LDA(At, 1, 1); PG8_STAGE(PG8_SA(1, 0), a3, voffA);
;             PG8_BAR; PG8_WAIT_L(0); PG8_MMA(1, 0, At, B0); PG8_BAR; PG8_SCHED;
;             PG8_STAGE(PG8_SB(1, 1), b3 + hstep, voffB);
;             PG8_WAIT_V(6); PG8_BAR; PG8_MMA(1, 1, At, B1); PG8_BAR;
;         }
	s_waitcnt lgkmcnt(0)
	s_setprio 1
	v_mfma_f32_16x16x32_bf16 v[124:127], v[144:147], v[168:171], v[124:127]
	v_mfma_f32_16x16x32_bf16 v[120:123], v[160:163], v[168:171], v[120:123]
	v_mfma_f32_16x16x32_bf16 v[116:119], v[144:147], v[188:191], v[116:119]
	v_mfma_f32_16x16x32_bf16 v[112:115], v[160:163], v[188:191], v[112:115]
	v_mfma_f32_16x16x32_bf16 v[100:103], v[144:147], v[196:199], v[100:103]
	v_mfma_f32_16x16x32_bf16 v[96:99], v[160:163], v[196:199], v[96:99]
	v_mfma_f32_16x16x32_bf16 v[84:87], v[144:147], v[204:207], v[84:87]
	v_mfma_f32_16x16x32_bf16 v[80:83], v[160:163], v[204:207], v[80:83]
	v_mfma_f32_16x16x32_bf16 v[124:127], v[148:151], v[184:187], v[124:127]
	v_mfma_f32_16x16x32_bf16 v[120:123], v[164:167], v[184:187], v[120:123]
	v_mfma_f32_16x16x32_bf16 v[116:119], v[148:151], v[192:195], v[116:119]
	v_mfma_f32_16x16x32_bf16 v[112:115], v[164:167], v[192:195], v[112:115]
	v_mfma_f32_16x16x32_bf16 v[100:103], v[148:151], v[200:203], v[100:103]
	v_mfma_f32_16x16x32_bf16 v[96:99], v[164:167], v[200:203], v[96:99]
	v_mfma_f32_16x16x32_bf16 v[84:87], v[148:151], v[208:211], v[84:87]
	v_mfma_f32_16x16x32_bf16 v[80:83], v[164:167], v[208:211], v[80:83]
	s_setprio 0
	s_barrier
	s_add_i32 s17, 0, 0x1c000
	s_add_i32 s1, s1, s85
	v_add_u32_e32 v183, s17, v141
	v_lshl_add_u64 v[152:153], v[152:153], 0, s[8:9]
	s_mov_b32 m0, s1
	ds_read_b128 v[212:215], v183
	ds_read_b128 v[216:219], v183 offset:1024
	ds_read_b128 v[220:223], v183 offset:2048
	ds_read_b128 v[224:227], v183 offset:3072
	global_load_lds_dwordx4 v[152:153], off
	v_lshl_add_u64 v[152:153], v[228:229], 0, s[8:9]
	s_add_i32 m0, s1, 0x2000
	s_nop 0
	global_load_lds_dwordx4 v[152:153], off
	s_barrier
	s_waitcnt lgkmcnt(0)
	s_setprio 1
	v_mfma_f32_16x16x32_bf16 v[108:111], v[212:215], v[168:171], v[108:111]
	v_mfma_f32_16x16x32_bf16 v[104:107], v[220:223], v[168:171], v[104:107]
	v_mfma_f32_16x16x32_bf16 v[92:95], v[212:215], v[188:191], v[92:95]
	s_mov_b32 m0, s92
	v_mfma_f32_16x16x32_bf16 v[88:91], v[220:223], v[188:191], v[88:91]
	v_lshl_add_u64 v[152:153], v[230:231], 0, s[8:9]
	v_mfma_f32_16x16x32_bf16 v[76:79], v[212:215], v[196:199], v[76:79]
	v_mfma_f32_16x16x32_bf16 v[72:75], v[220:223], v[196:199], v[72:75]
	v_mfma_f32_16x16x32_bf16 v[68:71], v[212:215], v[204:207], v[68:71]
	v_mfma_f32_16x16x32_bf16 v[64:67], v[220:223], v[204:207], v[64:67]
	v_mfma_f32_16x16x32_bf16 v[108:111], v[216:219], v[184:187], v[108:111]
	v_mfma_f32_16x16x32_bf16 v[104:107], v[224:227], v[184:187], v[104:107]
	v_mfma_f32_16x16x32_bf16 v[92:95], v[216:219], v[192:195], v[92:95]
	v_mfma_f32_16x16x32_bf16 v[88:91], v[224:227], v[192:195], v[88:91]
	v_mfma_f32_16x16x32_bf16 v[76:79], v[216:219], v[200:203], v[76:79]
	v_mfma_f32_16x16x32_bf16 v[72:75], v[224:227], v[200:203], v[72:75]
	v_mfma_f32_16x16x32_bf16 v[68:71], v[216:219], v[208:211], v[68:71]
	v_mfma_f32_16x16x32_bf16 v[64:67], v[224:227], v[208:211], v[64:67]
	s_setprio 0
	s_barrier
	ds_read_b128 v[168:171], v143 offset:49152
	ds_read_b128 v[184:187], v143 offset:50176
	ds_read_b128 v[188:191], v143 offset:51200
	ds_read_b128 v[192:195], v143 offset:52224
	ds_read_b128 v[196:199], v143 offset:53248
	ds_read_b128 v[200:203], v143 offset:54272
	ds_read_b128 v[204:207], v143 offset:55296
	ds_read_b128 v[208:211], v143 offset:56320
	global_load_lds_dwordx4 v[152:153], off
	v_lshl_add_u64 v[152:153], v[232:233], 0, s[8:9]
	s_mov_b32 m0, s93
	s_nop 0
	global_load_lds_dwordx4 v[152:153], off
	s_barrier
	s_waitcnt lgkmcnt(0)
	s_setprio 1
	v_mfma_f32_16x16x32_bf16 v[60:63], v[144:147], v[168:171], v[60:63]
	v_mfma_f32_16x16x32_bf16 v[56:59], v[160:163], v[168:171], v[56:59]
	v_mfma_f32_16x16x32_bf16 v[52:55], v[144:147], v[188:191], v[52:55]
	v_mfma_f32_16x16x32_bf16 v[48:51], v[160:163], v[188:191], v[48:51]
	v_mfma_f32_16x16x32_bf16 v[36:39], v[144:147], v[196:199], v[36:39]
	v_mfma_f32_16x16x32_bf16 v[32:35], v[160:163], v[196:199], v[32:35]
	v_mfma_f32_16x16x32_bf16 v[20:23], v[144:147], v[204:207], v[20:23]
	v_mfma_f32_16x16x32_bf16 v[16:19], v[160:163], v[204:207], v[16:19]
	v_mfma_f32_16x16x32_bf16 v[60:63], v[148:151], v[184:187], v[60:63]
	v_mfma_f32_16x16x32_bf16 v[56:59], v[164:167], v[184:187], v[56:59]
	v_mfma_f32_16x16x32_bf16 v[52:55], v[148:151], v[192:195], v[52:55]
	v_mfma_f32_16x16x32_bf16 v[48:51], v[164:167], v[192:195], v[48:51]
	v_mfma_f32_16x16x32_bf16 v[36:39], v[148:151], v[200:203], v[36:39]
	v_mfma_f32_16x16x32_bf16 v[32:35], v[164:167], v[200:203], v[32:35]
	v_mfma_f32_16x16x32_bf16 v[20:23], v[148:151], v[208:211], v[20:23]
	v_mfma_f32_16x16x32_bf16 v[16:19], v[164:167], v[208:211], v[16:19]
	s_setprio 0
	s_barrier
	s_add_i32 s1, s17, s85
	v_lshl_add_u64 v[144:145], v[234:235], 0, s[8:9]
	s_mov_b32 m0, s1
	s_nop 0
	global_load_lds_dwordx4 v[144:145], off
	v_lshl_add_u64 v[144:145], v[236:237], 0, s[8:9]
	s_add_i32 m0, s1, 0x2000
	s_nop 0
	global_load_lds_dwordx4 v[144:145], off
	s_waitcnt vmcnt(6)
	s_barrier
	s_setprio 1
	v_mfma_f32_16x16x32_bf16 v[44:47], v[212:215], v[168:171], v[44:47]
	v_mfma_f32_16x16x32_bf16 v[40:43], v[220:223], v[168:171], v[40:43]
	v_mfma_f32_16x16x32_bf16 v[28:31], v[212:215], v[188:191], v[28:31]
	s_add_u32 vcc_lo, vcc_lo, 0x100
	v_mfma_f32_16x16x32_bf16 v[24:27], v[220:223], v[188:191], v[24:27]
	s_addc_u32 vcc_hi, vcc_hi, 0
	v_mfma_f32_16x16x32_bf16 v[12:15], v[212:215], v[196:199], v[12:15]
	s_add_u32 s96, s96, 0x100
	v_mfma_f32_16x16x32_bf16 v[8:11], v[220:223], v[196:199], v[8:11]
	s_addc_u32 s65, s65, 0
	v_mfma_f32_16x16x32_bf16 v[4:7], v[212:215], v[204:207], v[4:7]
	s_cmp_ge_u32 s0, s94
	v_mfma_f32_16x16x32_bf16 v[0:3], v[220:223], v[204:207], v[0:3]
	s_mov_b32 s34, s0
	v_mfma_f32_16x16x32_bf16 v[44:47], v[216:219], v[184:187], v[44:47]
	v_mfma_f32_16x16x32_bf16 v[40:43], v[224:227], v[184:187], v[40:43]
	v_mfma_f32_16x16x32_bf16 v[28:31], v[216:219], v[192:195], v[28:31]
	v_mfma_f32_16x16x32_bf16 v[24:27], v[224:227], v[192:195], v[24:27]
	v_mfma_f32_16x16x32_bf16 v[12:15], v[216:219], v[200:203], v[12:15]
	v_mfma_f32_16x16x32_bf16 v[8:11], v[224:227], v[200:203], v[8:11]
	v_mfma_f32_16x16x32_bf16 v[4:7], v[216:219], v[208:211], v[4:7]
	v_mfma_f32_16x16x32_bf16 v[0:3], v[224:227], v[208:211], v[0:3]
	s_setprio 0
	s_barrier
	s_cbranch_scc0 .LBB0_100

; #define PG8_STAGE(bufoff, gbase, voff) do { _Pragma("unroll") for (int _i = 0; _i < 2; ++_i) \
;         __builtin_amdgcn_global_load_lds((const unsigned*)((const char*)(gbase) + (voff)[_i]), (LAS unsigned*)(lds + (bufoff) + ldsw + _i * 8192), 16, 0, 0); } while (0)
; #define PG8_LDA(dst, b, h) do { _Pragma("unroll") for (int m = 0; m < 4; ++m) _Pragma("unroll") for (int k = 0; k < 2; ++k) dst[m][k] = *(const LAS bf16x8*)(lds + PG8_SA(b, h) + aoff + m * 2048 + k * 1024); } while (0)
; #define PG8_LDB(dst, b, h) do { _Pragma("unroll") for (int n = 0; n < 2; ++n) _Pragma("unroll") for (int k = 0; k < 2; ++k) dst[n][k] = *(const LAS bf16x8*)(lds + PG8_SB(b, h) + boff + n * 2048 + k * 1024); } while (0)
; #define PG8_MMA(ai, bj, At, Bt) do { __builtin_amdgcn_s_setprio(1); _Pragma("unroll") for (int m = 0; m < 4; ++m) _Pragma("unroll") for (int n = 0; n < 2; ++n) _Pragma("unroll") for (int k = 0; k < 2; ++k) \
;         acc[ai][bj][m][n] = __builtin_amdgcn_mfma_f32_16x16x32_bf16(Bt[n][k], At[m][k], acc[ai][bj][m][n], 0, 0, 0); __builtin_amdgcn_s_setprio(0); } while (0)
; #define PG8_WAIT_L(n) asm volatile("s_waitcnt lgkmcnt(" #n ")" ::: "memory")
; template <class Epi, class Sched>
; __device__ __forceinline__ void gemm_phase(LAS unsigned char* lds, const Gemm g, const Sched& S, const Epi& E, int tid) {
;     ...
;         const bool has_next = S.next(ui + 1, nxt);
;         const char* nA = has_next ? (const char*)g.A + (size_t)nxt.pm * tstep : cA; const char* nB = has_next ? (const char*)g.Bt + (size_t)nxt.pn * tstep : cB;
;         for (int t = 0; t < nt; t += 2) {
;             const bool last = (t == nt - 2);
;             const char* a1 = cA + (size_t)(t + 1) * kstep;
;             const char* a2 = last ? nA : cA + (size_t)(t + 2) * kstep; const char* b2 = last ? nB : cB + (size_t)(t + 2) * kstep;
;             const char* a3 = a2 + kstep; const char* b3 = b2 + kstep;
;             PG8_LDB(B0, 0, 0); PG8_SCHED; PG8_LDA(At, 0, 0); PG8_STAGE(PG8_SA(1, 1), a1 + hstep, voffA);
;             PG8_WAIT_L(8); PG8_BAR; PG8_WAIT_L(0); PG8_MMA(0, 0, At, B0); PG8_BAR; PG8_SCHED;
;             PG8_LDB(B1, 0, 1); PG8_STAGE(PG8_SB(0, 0), b2, voffB);
;             PG8_BAR; PG8_WAIT_L(0); PG8_MMA(0, 1, At, B1); PG8_BAR;
;             PG8_LDA(At, 0, 1); PG8_STAGE(PG8_SA(0, 0), a2, voffA);
;             PG8_BAR; PG8_WAIT_L(0); PG8_MMA(1, 0, At, B0); PG8_BAR; PG8_SCHED;
.LBB0_114:
	s_ashr_i32 s25, s24, 31
	s_lshl_b64 s[0:1], s[24:25], 19
	v_cmp_lt_i64_e32 vcc, s[28:29], v[158:159]
	s_add_u32 s28, s26, s0
	s_addc_u32 s29, s27, s1
	s_and_b64 s[0:1], vcc, exec
	s_cselect_b32 s25, s29, s41
	s_cselect_b32 s53, s28, s40
	s_ashr_i32 s15, s14, 31
	s_lshl_b64 s[0:1], s[14:15], 19
	s_add_u32 s30, s19, s0
	s_addc_u32 s31, s44, s1
	s_and_b64 s[0:1], vcc, exec
	s_cselect_b32 s15, s31, s43
	s_cselect_b32 s55, s30, s42
	s_add_u32 s40, s40, 0x40080
	s_addc_u32 s41, s41, 0
	s_add_u32 s58, s42, 0x100
	s_addc_u32 s60, s43, 0
	s_mov_b32 s61, -2
	s_add_u32 s0, s40, 0xfffc0080
	s_addc_u32 s1, s41, -1
	s_add_i32 s17, 0, 0x10000
	v_add_u32_e32 v160, s17, v143
	ds_read_b128 v[138:141], v160
	ds_read_b128 v[146:149], v160 offset:1024
	ds_read_b128 v[150:153], v160 offset:2048
	ds_read_b128 v[160:163], v160 offset:3072
	s_cmp_eq_u32 s61, 12
	s_cselect_b32 s43, s25, s1
	s_cselect_b32 s42, s53, s0
	s_cselect_b32 s35, s15, s60
	s_cselect_b32 s34, s55, s58
	v_lshl_add_u64 v[208:209], s[40:41], 0, v[134:135]
	s_add_i32 m0, s39, 0xc000
	ds_read_b128 v[164:167], v145
	ds_read_b128 v[168:171], v145 offset:1024
	ds_read_b128 v[184:187], v145 offset:2048
	ds_read_b128 v[188:191], v145 offset:3072
	ds_read_b128 v[192:195], v145 offset:4096
	ds_read_b128 v[196:199], v145 offset:5120
	ds_read_b128 v[200:203], v145 offset:6144
	ds_read_b128 v[204:207], v145 offset:7168
	global_load_lds_dwordx4 v[208:209], off
	v_lshl_add_u64 v[208:209], s[40:41], 0, v[136:137]
	s_add_i32 m0, s39, 0xe000
	s_nop 0
	global_load_lds_dwordx4 v[208:209], off
	s_waitcnt lgkmcnt(8)
	s_barrier
	s_waitcnt lgkmcnt(0)
	s_setprio 1
	v_mfma_f32_16x16x32_bf16 v[124:127], v[138:141], v[164:167], 0
	v_mfma_f32_16x16x32_bf16 v[120:123], v[150:153], v[164:167], 0
	v_mfma_f32_16x16x32_bf16 v[108:111], v[138:141], v[184:187], 0
	v_mfma_f32_16x16x32_bf16 v[104:107], v[150:153], v[184:187], 0
	v_mfma_f32_16x16x32_bf16 v[92:95], v[138:141], v[192:195], 0
	v_mfma_f32_16x16x32_bf16 v[88:91], v[150:153], v[192:195], 0
	v_mfma_f32_16x16x32_bf16 v[76:79], v[138:141], v[200:203], 0
	v_mfma_f32_16x16x32_bf16 v[72:75], v[150:153], v[200:203], 0
	v_mfma_f32_16x16x32_bf16 v[124:127], v[146:149], v[168:171], v[124:127]
	v_mfma_f32_16x16x32_bf16 v[120:123], v[160:163], v[168:171], v[120:123]
	v_mfma_f32_16x16x32_bf16 v[108:111], v[146:149], v[188:191], v[108:111]
	v_mfma_f32_16x16x32_bf16 v[104:107], v[160:163], v[188:191], v[104:107]
	v_mfma_f32_16x16x32_bf16 v[92:95], v[146:149], v[196:199], v[92:95]
	v_mfma_f32_16x16x32_bf16 v[88:91], v[160:163], v[196:199], v[88:91]
	v_mfma_f32_16x16x32_bf16 v[76:79], v[146:149], v[204:207], v[76:79]
	v_mfma_f32_16x16x32_bf16 v[72:75], v[160:163], v[204:207], v[72:75]
	s_setprio 0
	s_barrier
	s_add_i32 s63, 0, 0x14000
	s_add_i32 s0, s17, s45
	v_add_u32_e32 v183, s63, v143
	v_lshl_add_u64 v[224:225], s[34:35], 0, v[154:155]
	s_mov_b32 m0, s0
	ds_read_b128 v[208:211], v183
	ds_read_b128 v[212:215], v183 offset:1024
	ds_read_b128 v[216:219], v183 offset:2048
	ds_read_b128 v[220:223], v183 offset:3072
	global_load_lds_dwordx4 v[224:225], off
	v_lshl_add_u64 v[226:227], s[34:35], 0, v[128:129]
	s_add_i32 m0, s0, 0x2000
	s_nop 0
	global_load_lds_dwordx4 v[226:227], off
	s_barrier
	s_waitcnt lgkmcnt(0)
	s_setprio 1
	v_mfma_f32_16x16x32_bf16 v[116:119], v[208:211], v[164:167], 0
	v_mfma_f32_16x16x32_bf16 v[112:115], v[216:219], v[164:167], 0
	v_mfma_f32_16x16x32_bf16 v[100:103], v[208:211], v[184:187], 0
	s_mov_b32 m0, s39
	v_mfma_f32_16x16x32_bf16 v[96:99], v[216:219], v[184:187], 0
	v_lshl_add_u64 v[228:229], s[42:43], 0, v[132:133]
	v_mfma_f32_16x16x32_bf16 v[84:87], v[208:211], v[192:195], 0
	v_mfma_f32_16x16x32_bf16 v[80:83], v[216:219], v[192:195], 0
	v_mfma_f32_16x16x32_bf16 v[68:71], v[208:211], v[200:203], 0
	v_mfma_f32_16x16x32_bf16 v[64:67], v[216:219], v[200:203], 0
	v_mfma_f32_16x16x32_bf16 v[116:119], v[212:215], v[168:171], v[116:119]
	v_mfma_f32_16x16x32_bf16 v[112:115], v[220:223], v[168:171], v[112:115]
	v_mfma_f32_16x16x32_bf16 v[100:103], v[212:215], v[188:191], v[100:103]
	v_mfma_f32_16x16x32_bf16 v[96:99], v[220:223], v[188:191], v[96:99]
	v_mfma_f32_16x16x32_bf16 v[84:87], v[212:215], v[196:199], v[84:87]
	v_mfma_f32_16x16x32_bf16 v[80:83], v[220:223], v[196:199], v[80:83]
	v_mfma_f32_16x16x32_bf16 v[68:71], v[212:215], v[204:207], v[68:71]
	v_mfma_f32_16x16x32_bf16 v[64:67], v[220:223], v[204:207], v[64:67]
	s_setprio 0
	s_barrier
	ds_read_b128 v[164:167], v145 offset:16384
	ds_read_b128 v[168:171], v145 offset:17408
	ds_read_b128 v[184:187], v145 offset:18432
	ds_read_b128 v[188:191], v145 offset:19456
	ds_read_b128 v[192:195], v145 offset:20480
	ds_read_b128 v[196:199], v145 offset:21504
	ds_read_b128 v[200:203], v145 offset:22528
	ds_read_b128 v[204:207], v145 offset:23552
	global_load_lds_dwordx4 v[228:229], off
	v_lshl_add_u64 v[230:231], s[42:43], 0, v[130:131]
	s_mov_b32 m0, s47
	s_nop 0
	global_load_lds_dwordx4 v[230:231], off
	s_barrier
	s_waitcnt lgkmcnt(0)
	s_setprio 1
	v_mfma_f32_16x16x32_bf16 v[60:63], v[138:141], v[164:167], 0
	v_mfma_f32_16x16x32_bf16 v[56:59], v[150:153], v[164:167], 0
	v_mfma_f32_16x16x32_bf16 v[44:47], v[138:141], v[184:187], 0
	v_mfma_f32_16x16x32_bf16 v[40:43], v[150:153], v[184:187], 0
	v_mfma_f32_16x16x32_bf16 v[28:31], v[138:141], v[192:195], 0
	v_mfma_f32_16x16x32_bf16 v[24:27], v[150:153], v[192:195], 0
	v_mfma_f32_16x16x32_bf16 v[12:15], v[138:141], v[200:203], 0
	v_mfma_f32_16x16x32_bf16 v[8:11], v[150:153], v[200:203], 0
	v_mfma_f32_16x16x32_bf16 v[60:63], v[146:149], v[168:171], v[60:63]
	v_mfma_f32_16x16x32_bf16 v[56:59], v[160:163], v[168:171], v[56:59]
	v_mfma_f32_16x16x32_bf16 v[44:47], v[146:149], v[188:191], v[44:47]
	v_mfma_f32_16x16x32_bf16 v[40:43], v[160:163], v[188:191], v[40:43]
	v_mfma_f32_16x16x32_bf16 v[28:31], v[146:149], v[196:199], v[28:31]
	v_mfma_f32_16x16x32_bf16 v[24:27], v[160:163], v[196:199], v[24:27]
	v_mfma_f32_16x16x32_bf16 v[12:15], v[146:149], v[204:207], v[12:15]
	v_mfma_f32_16x16x32_bf16 v[8:11], v[160:163], v[204:207], v[8:11]
	s_setprio 0
	s_barrier
; #define PG8_STAGE(bufoff, gbase, voff) do { _Pragma("unroll") for (int _i = 0; _i < 2; ++_i) \
;         __builtin_amdgcn_global_load_lds((const unsigned*)((const char*)(gbase) + (voff)[_i]), (LAS unsigned*)(lds + (bufoff) + ldsw + _i * 8192), 16, 0, 0); } while (0)
; #define PG8_LDA(dst, b, h) do { _Pragma("unroll") for (int m = 0; m < 4; ++m) _Pragma("unroll") for (int k = 0; k < 2; ++k) dst[m][k] = *(const LAS bf16x8*)(lds + PG8_SA(b, h) + aoff + m * 2048 + k * 1024); } while (0)
; #define PG8_LDB(dst, b, h) do { _Pragma("unroll") for (int n = 0; n < 2; ++n) _Pragma("unroll") for (int k = 0; k < 2; ++k) dst[n][k] = *(const LAS bf16x8*)(lds + PG8_SB(b, h) + boff + n * 2048 + k * 1024); } while (0)
; #define PG8_MMA(ai, bj, At, Bt) do { __builtin_amdgcn_s_setprio(1); _Pragma("unroll") for (int m = 0; m < 4; ++m) _Pragma("unroll") for (int n = 0; n < 2; ++n) _Pragma("unroll") for (int k = 0; k < 2; ++k) \
;         acc[ai][bj][m][n] = __builtin_amdgcn_mfma_f32_16x16x32_bf16(Bt[n][k], At[m][k], acc[ai][bj][m][n], 0, 0, 0); __builtin_amdgcn_s_setprio(0); } while (0)
; #define PG8_WAIT_V(n) asm volatile("s_waitcnt vmcnt(" #n ")" ::: "memory")
; #define PG8_WAIT_L(n) asm volatile("s_waitcnt lgkmcnt(" #n ")" ::: "memory")
; #define PG8_BAR __builtin_amdgcn_s_barrier()
; #define PG8_SCHED __builtin_amdgcn_sched_barrier(0)
; template <class Epi, class Sched>
; __device__ __forceinline__ void gemm_phase(LAS unsigned char* lds, const Gemm g, const Sched& S, const Epi& E, int tid) {
;     ...
;             PG8_STAGE(PG8_SB(0, 1), b2 + hstep, voffB);
;             PG8_WAIT_V(6); PG8_BAR; PG8_MMA(1, 1, At, B1); PG8_BAR;
;             PG8_LDB(B0, 1, 0); PG8_SCHED; PG8_LDA(At, 1, 0); PG8_STAGE(PG8_SA(0, 1), a2 + hstep, voffA);
;             PG8_WAIT_L(8); PG8_BAR; PG8_WAIT_L(0); PG8_MMA(0, 0, At, B0); PG8_BAR; PG8_SCHED;
;             PG8_LDB(B1, 1, 1); PG8_STAGE(PG8_SB(1, 0), b3, voffB);
;             PG8_BAR; PG8_WAIT_L(0); PG8_MMA(0, 1, At, B1); PG8_BAR;
;             PG8_LDA(At, 1, 1); PG8_STAGE(PG8_SA(1, 0), a3, voffA);
;             PG8_BAR; PG8_WAIT_L(0); PG8_MMA(1, 0, At, B0); PG8_BAR; PG8_SCHED;
	s_add_u32 s0, s34, 0x40000
	s_addc_u32 s1, s35, 0
	s_add_i32 s17, s63, s45
	v_lshl_add_u64 v[138:139], s[0:1], 0, v[154:155]
	s_mov_b32 m0, s17
	s_nop 0
	global_load_lds_dwordx4 v[138:139], off
	v_lshl_add_u64 v[138:139], s[0:1], 0, v[128:129]
	s_add_i32 m0, s17, 0x2000
	s_nop 0
	global_load_lds_dwordx4 v[138:139], off
	s_waitcnt vmcnt(16)
	s_barrier
	s_setprio 1
	v_mfma_f32_16x16x32_bf16 v[52:55], v[208:211], v[164:167], 0
	v_mfma_f32_16x16x32_bf16 v[48:51], v[216:219], v[164:167], 0
	v_mfma_f32_16x16x32_bf16 v[36:39], v[208:211], v[184:187], 0
	s_add_i32 s17, 0, 0x18000
	v_mfma_f32_16x16x32_bf16 v[32:35], v[216:219], v[184:187], 0
	v_add_u32_e32 v160, s17, v143
	v_mfma_f32_16x16x32_bf16 v[20:23], v[208:211], v[192:195], 0
	v_mfma_f32_16x16x32_bf16 v[16:19], v[216:219], v[192:195], 0
	v_mfma_f32_16x16x32_bf16 v[4:7], v[208:211], v[200:203], 0
	v_mfma_f32_16x16x32_bf16 v[0:3], v[216:219], v[200:203], 0
	v_mfma_f32_16x16x32_bf16 v[52:55], v[212:215], v[168:171], v[52:55]
	v_mfma_f32_16x16x32_bf16 v[48:51], v[220:223], v[168:171], v[48:51]
	v_mfma_f32_16x16x32_bf16 v[36:39], v[212:215], v[188:191], v[36:39]
	v_mfma_f32_16x16x32_bf16 v[32:35], v[220:223], v[188:191], v[32:35]
	v_mfma_f32_16x16x32_bf16 v[20:23], v[212:215], v[196:199], v[20:23]
	v_mfma_f32_16x16x32_bf16 v[16:19], v[220:223], v[196:199], v[16:19]
	v_mfma_f32_16x16x32_bf16 v[4:7], v[212:215], v[204:207], v[4:7]
	v_mfma_f32_16x16x32_bf16 v[0:3], v[220:223], v[204:207], v[0:3]
	s_setprio 0
	s_barrier
	ds_read_b128 v[138:141], v160
	ds_read_b128 v[146:149], v160 offset:1024
	ds_read_b128 v[150:153], v160 offset:2048
	ds_read_b128 v[160:163], v160 offset:3072
	s_add_u32 s0, s42, 0x40000
	s_addc_u32 s1, s43, 0
	s_mov_b32 m0, s48
	v_lshl_add_u64 v[208:209], s[0:1], 0, v[132:133]
	ds_read_b128 v[164:167], v145 offset:32768
	ds_read_b128 v[168:171], v145 offset:33792
	ds_read_b128 v[184:187], v145 offset:34816
	ds_read_b128 v[188:191], v145 offset:35840
	ds_read_b128 v[192:195], v145 offset:36864
	ds_read_b128 v[196:199], v145 offset:37888
	ds_read_b128 v[200:203], v145 offset:38912
	ds_read_b128 v[204:207], v145 offset:39936
	global_load_lds_dwordx4 v[208:209], off
	v_lshl_add_u64 v[208:209], s[0:1], 0, v[130:131]
	s_mov_b32 m0, s49
	s_nop 0
	global_load_lds_dwordx4 v[208:209], off
	s_waitcnt lgkmcnt(8)
	s_barrier
	s_waitcnt lgkmcnt(0)
	s_setprio 1
	v_mfma_f32_16x16x32_bf16 v[124:127], v[138:141], v[164:167], v[124:127]
	v_mfma_f32_16x16x32_bf16 v[120:123], v[150:153], v[164:167], v[120:123]
	v_mfma_f32_16x16x32_bf16 v[108:111], v[138:141], v[184:187], v[108:111]
	v_mfma_f32_16x16x32_bf16 v[104:107], v[150:153], v[184:187], v[104:107]
	v_mfma_f32_16x16x32_bf16 v[92:95], v[138:141], v[192:195], v[92:95]
	v_mfma_f32_16x16x32_bf16 v[88:91], v[150:153], v[192:195], v[88:91]
	v_mfma_f32_16x16x32_bf16 v[76:79], v[138:141], v[200:203], v[76:79]
	v_mfma_f32_16x16x32_bf16 v[72:75], v[150:153], v[200:203], v[72:75]
	v_mfma_f32_16x16x32_bf16 v[124:127], v[146:149], v[168:171], v[124:127]
	v_mfma_f32_16x16x32_bf16 v[120:123], v[160:163], v[168:171], v[120:123]
	v_mfma_f32_16x16x32_bf16 v[108:111], v[146:149], v[188:191], v[108:111]
	v_mfma_f32_16x16x32_bf16 v[104:107], v[160:163], v[188:191], v[104:107]
	v_mfma_f32_16x16x32_bf16 v[92:95], v[146:149], v[196:199], v[92:95]
	v_mfma_f32_16x16x32_bf16 v[88:91], v[160:163], v[196:199], v[88:91]
	v_mfma_f32_16x16x32_bf16 v[76:79], v[146:149], v[204:207], v[76:79]
	v_mfma_f32_16x16x32_bf16 v[72:75], v[160:163], v[204:207], v[72:75]
	s_setprio 0
	s_barrier
	s_add_i32 s42, 0, 0x1c000
	s_add_i32 s0, s17, s45
	v_add_u32_e32 v183, s42, v143
	v_lshl_add_u64 v[224:225], v[224:225], 0, s[8:9]
	s_mov_b32 m0, s0
	ds_read_b128 v[208:211], v183
	ds_read_b128 v[212:215], v183 offset:1024
	ds_read_b128 v[216:219], v183 offset:2048
	ds_read_b128 v[220:223], v183 offset:3072
	global_load_lds_dwordx4 v[224:225], off
	v_lshl_add_u64 v[224:225], v[226:227], 0, s[8:9]
	s_add_i32 m0, s0, 0x2000
	s_nop 0
	global_load_lds_dwordx4 v[224:225], off
	s_waitcnt vmcnt(10)
	s_barrier
	s_waitcnt lgkmcnt(0)
	s_setprio 1
	v_mfma_f32_16x16x32_bf16 v[116:119], v[208:211], v[164:167], v[116:119]
	v_mfma_f32_16x16x32_bf16 v[112:115], v[216:219], v[164:167], v[112:115]
	v_mfma_f32_16x16x32_bf16 v[100:103], v[208:211], v[184:187], v[100:103]
	s_mov_b32 m0, s6
	v_mfma_f32_16x16x32_bf16 v[96:99], v[216:219], v[184:187], v[96:99]
	v_lshl_add_u64 v[224:225], v[228:229], 0, s[8:9]
	v_mfma_f32_16x16x32_bf16 v[84:87], v[208:211], v[192:195], v[84:87]
	v_mfma_f32_16x16x32_bf16 v[80:83], v[216:219], v[192:195], v[80:83]
	v_mfma_f32_16x16x32_bf16 v[68:71], v[208:211], v[200:203], v[68:71]
	v_mfma_f32_16x16x32_bf16 v[64:67], v[216:219], v[200:203], v[64:67]
	v_mfma_f32_16x16x32_bf16 v[116:119], v[212:215], v[168:171], v[116:119]
	v_mfma_f32_16x16x32_bf16 v[112:115], v[220:223], v[168:171], v[112:115]
	v_mfma_f32_16x16x32_bf16 v[100:103], v[212:215], v[188:191], v[100:103]
	v_mfma_f32_16x16x32_bf16 v[96:99], v[220:223], v[188:191], v[96:99]
	v_mfma_f32_16x16x32_bf16 v[84:87], v[212:215], v[196:199], v[84:87]
	v_mfma_f32_16x16x32_bf16 v[80:83], v[220:223], v[196:199], v[80:83]
	v_mfma_f32_16x16x32_bf16 v[68:71], v[212:215], v[204:207], v[68:71]
	v_mfma_f32_16x16x32_bf16 v[64:67], v[220:223], v[204:207], v[64:67]
	s_setprio 0
	s_barrier
	ds_read_b128 v[164:167], v145 offset:49152
	ds_read_b128 v[168:171], v145 offset:50176
	ds_read_b128 v[184:187], v145 offset:51200
	ds_read_b128 v[188:191], v145 offset:52224
	ds_read_b128 v[192:195], v145 offset:53248
	ds_read_b128 v[196:199], v145 offset:54272
	ds_read_b128 v[200:203], v145 offset:55296
	ds_read_b128 v[204:207], v145 offset:56320
	global_load_lds_dwordx4 v[224:225], off
	v_lshl_add_u64 v[224:225], v[230:231], 0, s[8:9]
	s_mov_b32 m0, s50
	s_nop 0
	global_load_lds_dwordx4 v[224:225], off
	s_barrier
; #define PG8_STAGE(bufoff, gbase, voff) do { _Pragma("unroll") for (int _i = 0; _i < 2; ++_i) \
;         __builtin_amdgcn_global_load_lds((const unsigned*)((const char*)(gbase) + (voff)[_i]), (LAS unsigned*)(lds + (bufoff) + ldsw + _i * 8192), 16, 0, 0); } while (0)
; #define PG8_LDA(dst, b, h) do { _Pragma("unroll") for (int m = 0; m < 4; ++m) _Pragma("unroll") for (int k = 0; k < 2; ++k) dst[m][k] = *(const LAS bf16x8*)(lds + PG8_SA(b, h) + aoff + m * 2048 + k * 1024); } while (0)
; #define PG8_LDB(dst, b, h) do { _Pragma("unroll") for (int n = 0; n < 2; ++n) _Pragma("unroll") for (int k = 0; k < 2; ++k) dst[n][k] = *(const LAS bf16x8*)(lds + PG8_SB(b, h) + boff + n * 2048 + k * 1024); } while (0)
; #define PG8_MMA(ai, bj, At, Bt) do { __builtin_amdgcn_s_setprio(1); _Pragma("unroll") for (int m = 0; m < 4; ++m) _Pragma("unroll") for (int n = 0; n < 2; ++n) _Pragma("unroll") for (int k = 0; k < 2; ++k) \
;         acc[ai][bj][m][n] = __builtin_amdgcn_mfma_f32_16x16x32_bf16(Bt[n][k], At[m][k], acc[ai][bj][m][n], 0, 0, 0); __builtin_amdgcn_s_setprio(0); } while (0)
; #define PG8_WAIT_V(n) asm volatile("s_waitcnt vmcnt(" #n ")" ::: "memory")
; #define PG8_WAIT_L(n) asm volatile("s_waitcnt lgkmcnt(" #n ")" ::: "memory")
; #define PG8_BAR __builtin_amdgcn_s_barrier()
; #define PG8_SCHED __builtin_amdgcn_sched_barrier(0)
; template <class Epi, class Sched>
; __device__ __forceinline__ void gemm_phase(LAS unsigned char* lds, const Gemm g, const Sched& S, const Epi& E, int tid) {
;     ...
;             const bool last = (t == nt - 2);
;             const char* a1 = cA + (size_t)(t + 1) * kstep;
;             const char* a2 = last ? nA : cA + (size_t)(t + 2) * kstep; const char* b2 = last ? nB : cB + (size_t)(t + 2) * kstep;
;             const char* a3 = a2 + kstep; const char* b3 = b2 + kstep;
;             PG8_LDB(B0, 0, 0); PG8_SCHED; PG8_LDA(At, 0, 0); PG8_STAGE(PG8_SA(1, 1), a1 + hstep, voffA);
;             PG8_WAIT_L(8); PG8_BAR; PG8_WAIT_L(0); PG8_MMA(0, 0, At, B0); PG8_BAR; PG8_SCHED;
;             PG8_LDB(B1, 0, 1); PG8_STAGE(PG8_SB(0, 0), b2, voffB);
;             PG8_BAR; PG8_WAIT_L(0); PG8_MMA(0, 1, At, B1); PG8_BAR;
;     ...
;             PG8_BAR; PG8_WAIT_L(0); PG8_MMA(1, 0, At, B0); PG8_BAR; PG8_SCHED;
;             PG8_STAGE(PG8_SB(1, 1), b3 + hstep, voffB);
;             PG8_WAIT_V(6); PG8_BAR; PG8_MMA(1, 1, At, B1); PG8_BAR;
	s_waitcnt lgkmcnt(0)
	s_setprio 1
	v_mfma_f32_16x16x32_bf16 v[60:63], v[138:141], v[164:167], v[60:63]
	v_mfma_f32_16x16x32_bf16 v[56:59], v[150:153], v[164:167], v[56:59]
	v_mfma_f32_16x16x32_bf16 v[44:47], v[138:141], v[184:187], v[44:47]
	v_mfma_f32_16x16x32_bf16 v[40:43], v[150:153], v[184:187], v[40:43]
	v_mfma_f32_16x16x32_bf16 v[28:31], v[138:141], v[192:195], v[28:31]
	v_mfma_f32_16x16x32_bf16 v[24:27], v[150:153], v[192:195], v[24:27]
	v_mfma_f32_16x16x32_bf16 v[12:15], v[138:141], v[200:203], v[12:15]
	v_mfma_f32_16x16x32_bf16 v[8:11], v[150:153], v[200:203], v[8:11]
	v_mfma_f32_16x16x32_bf16 v[60:63], v[146:149], v[168:171], v[60:63]
	v_mfma_f32_16x16x32_bf16 v[56:59], v[160:163], v[168:171], v[56:59]
	v_mfma_f32_16x16x32_bf16 v[44:47], v[146:149], v[188:191], v[44:47]
	v_mfma_f32_16x16x32_bf16 v[40:43], v[160:163], v[188:191], v[40:43]
	v_mfma_f32_16x16x32_bf16 v[28:31], v[146:149], v[196:199], v[28:31]
	v_mfma_f32_16x16x32_bf16 v[24:27], v[160:163], v[196:199], v[24:27]
	v_mfma_f32_16x16x32_bf16 v[12:15], v[146:149], v[204:207], v[12:15]
	v_mfma_f32_16x16x32_bf16 v[8:11], v[160:163], v[204:207], v[8:11]
	s_setprio 0
	s_barrier
	s_add_u32 s0, s34, 0x40080
	s_addc_u32 s1, s35, 0
	s_add_i32 s17, s42, s45
	v_lshl_add_u64 v[138:139], s[0:1], 0, v[154:155]
	s_mov_b32 m0, s17
	s_nop 0
	global_load_lds_dwordx4 v[138:139], off
	v_lshl_add_u64 v[138:139], s[0:1], 0, v[128:129]
	s_add_i32 m0, s17, 0x2000
	s_nop 0
	global_load_lds_dwordx4 v[138:139], off
	s_waitcnt vmcnt(6)
	s_barrier
	s_setprio 1
	v_mfma_f32_16x16x32_bf16 v[52:55], v[208:211], v[164:167], v[52:55]
	v_mfma_f32_16x16x32_bf16 v[48:51], v[216:219], v[164:167], v[48:51]
	v_mfma_f32_16x16x32_bf16 v[36:39], v[208:211], v[184:187], v[36:39]
	s_add_i32 s61, s61, 2
	v_mfma_f32_16x16x32_bf16 v[32:35], v[216:219], v[184:187], v[32:35]
	s_add_u32 s40, s40, 0x100
	v_mfma_f32_16x16x32_bf16 v[20:23], v[208:211], v[192:195], v[20:23]
	s_addc_u32 s41, s41, 0
	v_mfma_f32_16x16x32_bf16 v[16:19], v[216:219], v[192:195], v[16:19]
	s_add_u32 s58, s58, 0x100
	v_mfma_f32_16x16x32_bf16 v[4:7], v[208:211], v[200:203], v[4:7]
	s_addc_u32 s60, s60, 0
	v_mfma_f32_16x16x32_bf16 v[0:3], v[216:219], v[200:203], v[0:3]
	s_cmp_gt_u32 s61, 13
	v_mfma_f32_16x16x32_bf16 v[52:55], v[212:215], v[168:171], v[52:55]
	v_mfma_f32_16x16x32_bf16 v[48:51], v[220:223], v[168:171], v[48:51]
	v_mfma_f32_16x16x32_bf16 v[36:39], v[212:215], v[188:191], v[36:39]
	v_mfma_f32_16x16x32_bf16 v[32:35], v[220:223], v[188:191], v[32:35]
	v_mfma_f32_16x16x32_bf16 v[20:23], v[212:215], v[196:199], v[20:23]
	v_mfma_f32_16x16x32_bf16 v[16:19], v[220:223], v[196:199], v[16:19]
	v_mfma_f32_16x16x32_bf16 v[4:7], v[212:215], v[204:207], v[4:7]
	v_mfma_f32_16x16x32_bf16 v[0:3], v[220:223], v[204:207], v[0:3]
	s_setprio 0
	s_barrier
	s_cbranch_scc1 .Lpeel_exit_swiglu
.LBB0_115:
	s_add_u32 s0, s40, 0xfffc0080
	s_addc_u32 s1, s41, -1
	s_add_i32 s17, 0, 0x10000
	v_add_u32_e32 v160, s17, v143
	ds_read_b128 v[138:141], v160
	ds_read_b128 v[146:149], v160 offset:1024
	ds_read_b128 v[150:153], v160 offset:2048
	ds_read_b128 v[160:163], v160 offset:3072
	s_cmp_eq_u32 s61, 12
	s_cselect_b32 s43, s25, s1
	s_cselect_b32 s42, s53, s0
	s_cselect_b32 s35, s15, s60
	s_cselect_b32 s34, s55, s58
	v_lshl_add_u64 v[208:209], s[40:41], 0, v[134:135]
	s_add_i32 m0, s39, 0xc000
	ds_read_b128 v[164:167], v145
	ds_read_b128 v[168:171], v145 offset:1024
	ds_read_b128 v[184:187], v145 offset:2048
	ds_read_b128 v[188:191], v145 offset:3072
	ds_read_b128 v[192:195], v145 offset:4096
	ds_read_b128 v[196:199], v145 offset:5120
	ds_read_b128 v[200:203], v145 offset:6144
	ds_read_b128 v[204:207], v145 offset:7168
	global_load_lds_dwordx4 v[208:209], off
	v_lshl_add_u64 v[208:209], s[40:41], 0, v[136:137]
	s_add_i32 m0, s39, 0xe000
	s_nop 0
	global_load_lds_dwordx4 v[208:209], off
	s_waitcnt lgkmcnt(8)
	s_barrier
	s_waitcnt lgkmcnt(0)
	s_setprio 1
	v_mfma_f32_16x16x32_bf16 v[124:127], v[138:141], v[164:167], v[124:127]
	v_mfma_f32_16x16x32_bf16 v[120:123], v[150:153], v[164:167], v[120:123]
	v_mfma_f32_16x16x32_bf16 v[108:111], v[138:141], v[184:187], v[108:111]
	v_mfma_f32_16x16x32_bf16 v[104:107], v[150:153], v[184:187], v[104:107]
	v_mfma_f32_16x16x32_bf16 v[92:95], v[138:141], v[192:195], v[92:95]
	v_mfma_f32_16x16x32_bf16 v[88:91], v[150:153], v[192:195], v[88:91]
	v_mfma_f32_16x16x32_bf16 v[76:79], v[138:141], v[200:203], v[76:79]
	v_mfma_f32_16x16x32_bf16 v[72:75], v[150:153], v[200:203], v[72:75]
	v_mfma_f32_16x16x32_bf16 v[124:127], v[146:149], v[168:171], v[124:127]
	v_mfma_f32_16x16x32_bf16 v[120:123], v[160:163], v[168:171], v[120:123]
	v_mfma_f32_16x16x32_bf16 v[108:111], v[146:149], v[188:191], v[108:111]
	v_mfma_f32_16x16x32_bf16 v[104:107], v[160:163], v[188:191], v[104:107]
	v_mfma_f32_16x16x32_bf16 v[92:95], v[146:149], v[196:199], v[92:95]
	v_mfma_f32_16x16x32_bf16 v[88:91], v[160:163], v[196:199], v[88:91]
	v_mfma_f32_16x16x32_bf16 v[76:79], v[146:149], v[204:207], v[76:79]
	v_mfma_f32_16x16x32_bf16 v[72:75], v[160:163], v[204:207], v[72:75]
	s_setprio 0
	s_barrier
	s_add_i32 s63, 0, 0x14000
	s_add_i32 s0, s17, s45
	v_add_u32_e32 v183, s63, v143
	v_lshl_add_u64 v[224:225], s[34:35], 0, v[154:155]
	s_mov_b32 m0, s0
	ds_read_b128 v[208:211], v183
	ds_read_b128 v[212:215], v183 offset:1024
	ds_read_b128 v[216:219], v183 offset:2048
	ds_read_b128 v[220:223], v183 offset:3072
	global_load_lds_dwordx4 v[224:225], off
	v_lshl_add_u64 v[226:227], s[34:35], 0, v[128:129]
	s_add_i32 m0, s0, 0x2000
	s_nop 0
	global_load_lds_dwordx4 v[226:227], off
	s_barrier
; #define PG8_STAGE(bufoff, gbase, voff) do { _Pragma("unroll") for (int _i = 0; _i < 2; ++_i) \
;         __builtin_amdgcn_global_load_lds((const unsigned*)((const char*)(gbase) + (voff)[_i]), (LAS unsigned*)(lds + (bufoff) + ldsw + _i * 8192), 16, 0, 0); } while (0)
; #define PG8_LDA(dst, b, h) do { _Pragma("unroll") for (int m = 0; m < 4; ++m) _Pragma("unroll") for (int k = 0; k < 2; ++k) dst[m][k] = *(const LAS bf16x8*)(lds + PG8_SA(b, h) + aoff + m * 2048 + k * 1024); } while (0)
; #define PG8_LDB(dst, b, h) do { _Pragma("unroll") for (int n = 0; n < 2; ++n) _Pragma("unroll") for (int k = 0; k < 2; ++k) dst[n][k] = *(const LAS bf16x8*)(lds + PG8_SB(b, h) + boff + n * 2048 + k * 1024); } while (0)
; #define PG8_MMA(ai, bj, At, Bt) do { __builtin_amdgcn_s_setprio(1); _Pragma("unroll") for (int m = 0; m < 4; ++m) _Pragma("unroll") for (int n = 0; n < 2; ++n) _Pragma("unroll") for (int k = 0; k < 2; ++k) \
;         acc[ai][bj][m][n] = __builtin_amdgcn_mfma_f32_16x16x32_bf16(Bt[n][k], At[m][k], acc[ai][bj][m][n], 0, 0, 0); __builtin_amdgcn_s_setprio(0); } while (0)
; #define PG8_WAIT_V(n) asm volatile("s_waitcnt vmcnt(" #n ")" ::: "memory")
; #define PG8_WAIT_L(n) asm volatile("s_waitcnt lgkmcnt(" #n ")" ::: "memory")
; #define PG8_BAR __builtin_amdgcn_s_barrier()
; #define PG8_SCHED __builtin_amdgcn_sched_barrier(0)
; template <class Epi, class Sched>
; __device__ __forceinline__ void gemm_phase(LAS unsigned char* lds, const Gemm g, const Sched& S, const Epi& E, int tid) {
;     ...
;             PG8_BAR; PG8_WAIT_L(0); PG8_MMA(0, 1, At, B1); PG8_BAR;
;             PG8_LDA(At, 0, 1); PG8_STAGE(PG8_SA(0, 0), a2, voffA);
;             PG8_BAR; PG8_WAIT_L(0); PG8_MMA(1, 0, At, B0); PG8_BAR; PG8_SCHED;
;             PG8_STAGE(PG8_SB(0, 1), b2 + hstep, voffB);
;             PG8_WAIT_V(6); PG8_BAR; PG8_MMA(1, 1, At, B1); PG8_BAR;
;             PG8_LDB(B0, 1, 0); PG8_SCHED; PG8_LDA(At, 1, 0); PG8_STAGE(PG8_SA(0, 1), a2 + hstep, voffA);
;             PG8_WAIT_L(8); PG8_BAR; PG8_WAIT_L(0); PG8_MMA(0, 0, At, B0); PG8_BAR; PG8_SCHED;
;             PG8_LDB(B1, 1, 1); PG8_STAGE(PG8_SB(1, 0), b3, voffB);
;             PG8_BAR; PG8_WAIT_L(0); PG8_MMA(0, 1, At, B1); PG8_BAR;
	s_waitcnt lgkmcnt(0)
	s_setprio 1
	v_mfma_f32_16x16x32_bf16 v[116:119], v[208:211], v[164:167], v[116:119]
	v_mfma_f32_16x16x32_bf16 v[112:115], v[216:219], v[164:167], v[112:115]
	v_mfma_f32_16x16x32_bf16 v[100:103], v[208:211], v[184:187], v[100:103]
	s_mov_b32 m0, s39
	v_mfma_f32_16x16x32_bf16 v[96:99], v[216:219], v[184:187], v[96:99]
	v_lshl_add_u64 v[228:229], s[42:43], 0, v[132:133]
	v_mfma_f32_16x16x32_bf16 v[84:87], v[208:211], v[192:195], v[84:87]
	v_mfma_f32_16x16x32_bf16 v[80:83], v[216:219], v[192:195], v[80:83]
	v_mfma_f32_16x16x32_bf16 v[68:71], v[208:211], v[200:203], v[68:71]
	v_mfma_f32_16x16x32_bf16 v[64:67], v[216:219], v[200:203], v[64:67]
	v_mfma_f32_16x16x32_bf16 v[116:119], v[212:215], v[168:171], v[116:119]
	v_mfma_f32_16x16x32_bf16 v[112:115], v[220:223], v[168:171], v[112:115]
	v_mfma_f32_16x16x32_bf16 v[100:103], v[212:215], v[188:191], v[100:103]
	v_mfma_f32_16x16x32_bf16 v[96:99], v[220:223], v[188:191], v[96:99]
	v_mfma_f32_16x16x32_bf16 v[84:87], v[212:215], v[196:199], v[84:87]
	v_mfma_f32_16x16x32_bf16 v[80:83], v[220:223], v[196:199], v[80:83]
	v_mfma_f32_16x16x32_bf16 v[68:71], v[212:215], v[204:207], v[68:71]
	v_mfma_f32_16x16x32_bf16 v[64:67], v[220:223], v[204:207], v[64:67]
	s_setprio 0
	s_barrier
	ds_read_b128 v[164:167], v145 offset:16384
	ds_read_b128 v[168:171], v145 offset:17408
	ds_read_b128 v[184:187], v145 offset:18432
	ds_read_b128 v[188:191], v145 offset:19456
	ds_read_b128 v[192:195], v145 offset:20480
	ds_read_b128 v[196:199], v145 offset:21504
	ds_read_b128 v[200:203], v145 offset:22528
	ds_read_b128 v[204:207], v145 offset:23552
	global_load_lds_dwordx4 v[228:229], off
	v_lshl_add_u64 v[230:231], s[42:43], 0, v[130:131]
	s_mov_b32 m0, s47
	s_nop 0
	global_load_lds_dwordx4 v[230:231], off
	s_barrier
	s_waitcnt lgkmcnt(0)
	s_setprio 1
	v_mfma_f32_16x16x32_bf16 v[60:63], v[138:141], v[164:167], v[60:63]
	v_mfma_f32_16x16x32_bf16 v[56:59], v[150:153], v[164:167], v[56:59]
	v_mfma_f32_16x16x32_bf16 v[44:47], v[138:141], v[184:187], v[44:47]
	v_mfma_f32_16x16x32_bf16 v[40:43], v[150:153], v[184:187], v[40:43]
	v_mfma_f32_16x16x32_bf16 v[28:31], v[138:141], v[192:195], v[28:31]
	v_mfma_f32_16x16x32_bf16 v[24:27], v[150:153], v[192:195], v[24:27]
	v_mfma_f32_16x16x32_bf16 v[12:15], v[138:141], v[200:203], v[12:15]
	v_mfma_f32_16x16x32_bf16 v[8:11], v[150:153], v[200:203], v[8:11]
	v_mfma_f32_16x16x32_bf16 v[60:63], v[146:149], v[168:171], v[60:63]
	v_mfma_f32_16x16x32_bf16 v[56:59], v[160:163], v[168:171], v[56:59]
	v_mfma_f32_16x16x32_bf16 v[44:47], v[146:149], v[188:191], v[44:47]
	v_mfma_f32_16x16x32_bf16 v[40:43], v[160:163], v[188:191], v[40:43]
	v_mfma_f32_16x16x32_bf16 v[28:31], v[146:149], v[196:199], v[28:31]
	v_mfma_f32_16x16x32_bf16 v[24:27], v[160:163], v[196:199], v[24:27]
	v_mfma_f32_16x16x32_bf16 v[12:15], v[146:149], v[204:207], v[12:15]
	v_mfma_f32_16x16x32_bf16 v[8:11], v[160:163], v[204:207], v[8:11]
	s_setprio 0
	s_barrier
	s_add_u32 s0, s34, 0x40000
	s_addc_u32 s1, s35, 0
	s_add_i32 s17, s63, s45
	v_lshl_add_u64 v[138:139], s[0:1], 0, v[154:155]
	s_mov_b32 m0, s17
	s_nop 0
	global_load_lds_dwordx4 v[138:139], off
	v_lshl_add_u64 v[138:139], s[0:1], 0, v[128:129]
	s_add_i32 m0, s17, 0x2000
	s_nop 0
	global_load_lds_dwordx4 v[138:139], off
	s_waitcnt vmcnt(6)
	s_barrier
	s_setprio 1
	v_mfma_f32_16x16x32_bf16 v[52:55], v[208:211], v[164:167], v[52:55]
	v_mfma_f32_16x16x32_bf16 v[48:51], v[216:219], v[164:167], v[48:51]
	v_mfma_f32_16x16x32_bf16 v[36:39], v[208:211], v[184:187], v[36:39]
	s_add_i32 s17, 0, 0x18000
	v_mfma_f32_16x16x32_bf16 v[32:35], v[216:219], v[184:187], v[32:35]
	v_add_u32_e32 v160, s17, v143
	v_mfma_f32_16x16x32_bf16 v[20:23], v[208:211], v[192:195], v[20:23]
	v_mfma_f32_16x16x32_bf16 v[16:19], v[216:219], v[192:195], v[16:19]
	v_mfma_f32_16x16x32_bf16 v[4:7], v[208:211], v[200:203], v[4:7]
	v_mfma_f32_16x16x32_bf16 v[0:3], v[216:219], v[200:203], v[0:3]
	v_mfma_f32_16x16x32_bf16 v[52:55], v[212:215], v[168:171], v[52:55]
	v_mfma_f32_16x16x32_bf16 v[48:51], v[220:223], v[168:171], v[48:51]
	v_mfma_f32_16x16x32_bf16 v[36:39], v[212:215], v[188:191], v[36:39]
	v_mfma_f32_16x16x32_bf16 v[32:35], v[220:223], v[188:191], v[32:35]
	v_mfma_f32_16x16x32_bf16 v[20:23], v[212:215], v[196:199], v[20:23]
	v_mfma_f32_16x16x32_bf16 v[16:19], v[220:223], v[196:199], v[16:19]
	v_mfma_f32_16x16x32_bf16 v[4:7], v[212:215], v[204:207], v[4:7]
	v_mfma_f32_16x16x32_bf16 v[0:3], v[220:223], v[204:207], v[0:3]
	s_setprio 0
	s_barrier
	ds_read_b128 v[138:141], v160
	ds_read_b128 v[146:149], v160 offset:1024
	ds_read_b128 v[150:153], v160 offset:2048
	ds_read_b128 v[160:163], v160 offset:3072
	s_add_u32 s0, s42, 0x40000
	s_addc_u32 s1, s43, 0
	s_mov_b32 m0, s48
	v_lshl_add_u64 v[208:209], s[0:1], 0, v[132:133]
	ds_read_b128 v[164:167], v145 offset:32768
	ds_read_b128 v[168:171], v145 offset:33792
	ds_read_b128 v[184:187], v145 offset:34816
	ds_read_b128 v[188:191], v145 offset:35840
	ds_read_b128 v[192:195], v145 offset:36864
	ds_read_b128 v[196:199], v145 offset:37888
	ds_read_b128 v[200:203], v145 offset:38912
	ds_read_b128 v[204:207], v145 offset:39936
	global_load_lds_dwordx4 v[208:209], off
	v_lshl_add_u64 v[208:209], s[0:1], 0, v[130:131]
	s_mov_b32 m0, s49
	s_nop 0
	global_load_lds_dwordx4 v[208:209], off
	s_waitcnt lgkmcnt(8)
	s_barrier
; #define PG8_STAGE(bufoff, gbase, voff) do { _Pragma("unroll") for (int _i = 0; _i < 2; ++_i) \
;         __builtin_amdgcn_global_load_lds((const unsigned*)((const char*)(gbase) + (voff)[_i]), (LAS unsigned*)(lds + (bufoff) + ldsw + _i * 8192), 16, 0, 0); } while (0)
; #define PG8_LDA(dst, b, h) do { _Pragma("unroll") for (int m = 0; m < 4; ++m) _Pragma("unroll") for (int k = 0; k < 2; ++k) dst[m][k] = *(const LAS bf16x8*)(lds + PG8_SA(b, h) + aoff + m * 2048 + k * 1024); } while (0)
; #define PG8_MMA(ai, bj, At, Bt) do { __builtin_amdgcn_s_setprio(1); _Pragma("unroll") for (int m = 0; m < 4; ++m) _Pragma("unroll") for (int n = 0; n < 2; ++n) _Pragma("unroll") for (int k = 0; k < 2; ++k) \
;         acc[ai][bj][m][n] = __builtin_amdgcn_mfma_f32_16x16x32_bf16(Bt[n][k], At[m][k], acc[ai][bj][m][n], 0, 0, 0); __builtin_amdgcn_s_setprio(0); } while (0)
; #define PG8_WAIT_V(n) asm volatile("s_waitcnt vmcnt(" #n ")" ::: "memory")
; #define PG8_WAIT_L(n) asm volatile("s_waitcnt lgkmcnt(" #n ")" ::: "memory")
; #define PG8_BAR __builtin_amdgcn_s_barrier()
; #define PG8_SCHED __builtin_amdgcn_sched_barrier(0)
; template <class Epi, class Sched>
; __device__ __forceinline__ void gemm_phase(LAS unsigned char* lds, const Gemm g, const Sched& S, const Epi& E, int tid) {
;     ...
;             PG8_BAR; PG8_WAIT_L(0); PG8_MMA(0, 1, At, B1); PG8_BAR;
;             PG8_LDA(At, 1, 1); PG8_STAGE(PG8_SA(1, 0), a3, voffA);
;             PG8_BAR; PG8_WAIT_L(0); PG8_MMA(1, 0, At, B0); PG8_BAR; PG8_SCHED;
;             PG8_STAGE(PG8_SB(1, 1), b3 + hstep, voffB);
;             PG8_WAIT_V(6); PG8_BAR; PG8_MMA(1, 1, At, B1); PG8_BAR;
;         }
	s_waitcnt lgkmcnt(0)
	s_setprio 1
	v_mfma_f32_16x16x32_bf16 v[124:127], v[138:141], v[164:167], v[124:127]
	v_mfma_f32_16x16x32_bf16 v[120:123], v[150:153], v[164:167], v[120:123]
	v_mfma_f32_16x16x32_bf16 v[108:111], v[138:141], v[184:187], v[108:111]
	v_mfma_f32_16x16x32_bf16 v[104:107], v[150:153], v[184:187], v[104:107]
	v_mfma_f32_16x16x32_bf16 v[92:95], v[138:141], v[192:195], v[92:95]
	v_mfma_f32_16x16x32_bf16 v[88:91], v[150:153], v[192:195], v[88:91]
	v_mfma_f32_16x16x32_bf16 v[76:79], v[138:141], v[200:203], v[76:79]
	v_mfma_f32_16x16x32_bf16 v[72:75], v[150:153], v[200:203], v[72:75]
	v_mfma_f32_16x16x32_bf16 v[124:127], v[146:149], v[168:171], v[124:127]
	v_mfma_f32_16x16x32_bf16 v[120:123], v[160:163], v[168:171], v[120:123]
	v_mfma_f32_16x16x32_bf16 v[108:111], v[146:149], v[188:191], v[108:111]
	v_mfma_f32_16x16x32_bf16 v[104:107], v[160:163], v[188:191], v[104:107]
	v_mfma_f32_16x16x32_bf16 v[92:95], v[146:149], v[196:199], v[92:95]
	v_mfma_f32_16x16x32_bf16 v[88:91], v[160:163], v[196:199], v[88:91]
	v_mfma_f32_16x16x32_bf16 v[76:79], v[146:149], v[204:207], v[76:79]
	v_mfma_f32_16x16x32_bf16 v[72:75], v[160:163], v[204:207], v[72:75]
	s_setprio 0
	s_barrier
	s_add_i32 s42, 0, 0x1c000
	s_add_i32 s0, s17, s45
	v_add_u32_e32 v183, s42, v143
	v_lshl_add_u64 v[224:225], v[224:225], 0, s[8:9]
	s_mov_b32 m0, s0
	ds_read_b128 v[208:211], v183
	ds_read_b128 v[212:215], v183 offset:1024
	ds_read_b128 v[216:219], v183 offset:2048
	ds_read_b128 v[220:223], v183 offset:3072
	global_load_lds_dwordx4 v[224:225], off
	v_lshl_add_u64 v[224:225], v[226:227], 0, s[8:9]
	s_add_i32 m0, s0, 0x2000
	s_nop 0
	global_load_lds_dwordx4 v[224:225], off
	s_barrier
	s_waitcnt lgkmcnt(0)
	s_setprio 1
	v_mfma_f32_16x16x32_bf16 v[116:119], v[208:211], v[164:167], v[116:119]
	v_mfma_f32_16x16x32_bf16 v[112:115], v[216:219], v[164:167], v[112:115]
	v_mfma_f32_16x16x32_bf16 v[100:103], v[208:211], v[184:187], v[100:103]
	s_mov_b32 m0, s6
	v_mfma_f32_16x16x32_bf16 v[96:99], v[216:219], v[184:187], v[96:99]
	v_lshl_add_u64 v[224:225], v[228:229], 0, s[8:9]
	v_mfma_f32_16x16x32_bf16 v[84:87], v[208:211], v[192:195], v[84:87]
	v_mfma_f32_16x16x32_bf16 v[80:83], v[216:219], v[192:195], v[80:83]
	v_mfma_f32_16x16x32_bf16 v[68:71], v[208:211], v[200:203], v[68:71]
	v_mfma_f32_16x16x32_bf16 v[64:67], v[216:219], v[200:203], v[64:67]
	v_mfma_f32_16x16x32_bf16 v[116:119], v[212:215], v[168:171], v[116:119]
	v_mfma_f32_16x16x32_bf16 v[112:115], v[220:223], v[168:171], v[112:115]
	v_mfma_f32_16x16x32_bf16 v[100:103], v[212:215], v[188:191], v[100:103]
	v_mfma_f32_16x16x32_bf16 v[96:99], v[220:223], v[188:191], v[96:99]
	v_mfma_f32_16x16x32_bf16 v[84:87], v[212:215], v[196:199], v[84:87]
	v_mfma_f32_16x16x32_bf16 v[80:83], v[220:223], v[196:199], v[80:83]
	v_mfma_f32_16x16x32_bf16 v[68:71], v[212:215], v[204:207], v[68:71]
	v_mfma_f32_16x16x32_bf16 v[64:67], v[220:223], v[204:207], v[64:67]
	s_setprio 0
	s_barrier
	ds_read_b128 v[164:167], v145 offset:49152
	ds_read_b128 v[168:171], v145 offset:50176
	ds_read_b128 v[184:187], v145 offset:51200
	ds_read_b128 v[188:191], v145 offset:52224
	ds_read_b128 v[192:195], v145 offset:53248
	ds_read_b128 v[196:199], v145 offset:54272
	ds_read_b128 v[200:203], v145 offset:55296
	ds_read_b128 v[204:207], v145 offset:56320
	global_load_lds_dwordx4 v[224:225], off
	v_lshl_add_u64 v[224:225], v[230:231], 0, s[8:9]
	s_mov_b32 m0, s50
	s_nop 0
	global_load_lds_dwordx4 v[224:225], off
	s_barrier
	s_waitcnt lgkmcnt(0)
	s_setprio 1
	v_mfma_f32_16x16x32_bf16 v[60:63], v[138:141], v[164:167], v[60:63]
	v_mfma_f32_16x16x32_bf16 v[56:59], v[150:153], v[164:167], v[56:59]
	v_mfma_f32_16x16x32_bf16 v[44:47], v[138:141], v[184:187], v[44:47]
	v_mfma_f32_16x16x32_bf16 v[40:43], v[150:153], v[184:187], v[40:43]
	v_mfma_f32_16x16x32_bf16 v[28:31], v[138:141], v[192:195], v[28:31]
	v_mfma_f32_16x16x32_bf16 v[24:27], v[150:153], v[192:195], v[24:27]
	v_mfma_f32_16x16x32_bf16 v[12:15], v[138:141], v[200:203], v[12:15]
	v_mfma_f32_16x16x32_bf16 v[8:11], v[150:153], v[200:203], v[8:11]
	v_mfma_f32_16x16x32_bf16 v[60:63], v[146:149], v[168:171], v[60:63]
	v_mfma_f32_16x16x32_bf16 v[56:59], v[160:163], v[168:171], v[56:59]
	v_mfma_f32_16x16x32_bf16 v[44:47], v[146:149], v[188:191], v[44:47]
	v_mfma_f32_16x16x32_bf16 v[40:43], v[160:163], v[188:191], v[40:43]
	v_mfma_f32_16x16x32_bf16 v[28:31], v[146:149], v[196:199], v[28:31]
	v_mfma_f32_16x16x32_bf16 v[24:27], v[160:163], v[196:199], v[24:27]
	v_mfma_f32_16x16x32_bf16 v[12:15], v[146:149], v[204:207], v[12:15]
	v_mfma_f32_16x16x32_bf16 v[8:11], v[160:163], v[204:207], v[8:11]
	s_setprio 0
	s_barrier
	s_add_u32 s0, s34, 0x40080
	s_addc_u32 s1, s35, 0
	s_add_i32 s17, s42, s45
	v_lshl_add_u64 v[138:139], s[0:1], 0, v[154:155]
	s_mov_b32 m0, s17
	s_nop 0
	global_load_lds_dwordx4 v[138:139], off
	v_lshl_add_u64 v[138:139], s[0:1], 0, v[128:129]
	s_add_i32 m0, s17, 0x2000
	s_nop 0
	global_load_lds_dwordx4 v[138:139], off
	s_waitcnt vmcnt(6)
	s_barrier
	s_setprio 1
	v_mfma_f32_16x16x32_bf16 v[52:55], v[208:211], v[164:167], v[52:55]
	v_mfma_f32_16x16x32_bf16 v[48:51], v[216:219], v[164:167], v[48:51]
	v_mfma_f32_16x16x32_bf16 v[36:39], v[208:211], v[184:187], v[36:39]
	s_add_i32 s61, s61, 2
	v_mfma_f32_16x16x32_bf16 v[32:35], v[216:219], v[184:187], v[32:35]
	s_add_u32 s40, s40, 0x100
	v_mfma_f32_16x16x32_bf16 v[20:23], v[208:211], v[192:195], v[20:23]
	s_addc_u32 s41, s41, 0
	v_mfma_f32_16x16x32_bf16 v[16:19], v[216:219], v[192:195], v[16:19]
	s_add_u32 s58, s58, 0x100
	v_mfma_f32_16x16x32_bf16 v[4:7], v[208:211], v[200:203], v[4:7]
	s_addc_u32 s60, s60, 0
	v_mfma_f32_16x16x32_bf16 v[0:3], v[216:219], v[200:203], v[0:3]
	s_cmp_gt_u32 s61, 13
	v_mfma_f32_16x16x32_bf16 v[52:55], v[212:215], v[168:171], v[52:55]
	v_mfma_f32_16x16x32_bf16 v[48:51], v[220:223], v[168:171], v[48:51]
	v_mfma_f32_16x16x32_bf16 v[36:39], v[212:215], v[188:191], v[36:39]
	v_mfma_f32_16x16x32_bf16 v[32:35], v[220:223], v[188:191], v[32:35]
	v_mfma_f32_16x16x32_bf16 v[20:23], v[212:215], v[196:199], v[20:23]
	v_mfma_f32_16x16x32_bf16 v[16:19], v[220:223], v[196:199], v[16:19]
	v_mfma_f32_16x16x32_bf16 v[4:7], v[212:215], v[204:207], v[4:7]
	v_mfma_f32_16x16x32_bf16 v[0:3], v[220:223], v[204:207], v[0:3]
	s_setprio 0
	s_barrier
	s_cbranch_scc0 .LBB0_115
